# v30 + swiglu epilogue no longer starts with vmcnt(0); counted vmcnt(8) after its 8 stores covers the cross-unit prefetch
# speedup vs baseline: 1.0014x; 1.0014x over previous
; __device__ __forceinline__ unsigned cvt_pk_bf16(float lo, float hi) { unsigned r; asm volatile("v_cvt_pk_bf16_f32 %0, %1, %2" : "=v"(r) : "v"(lo), "v"(hi)); return r; }
; __device__ __forceinline__ float silu_mul(float a, float b) { return a * b * __builtin_amdgcn_rcpf(1.0f + __builtin_amdgcn_exp2f(-a * LOG2E)); }
; __device__ __forceinline__ float row_rstd(const float* ss, int row) { return 1.0f / sqrtf(ss[row] * (1.0f / DM) + 1e-6f); }
;     __device__ __forceinline__ void operator()(const f32x4 (&acc)[2][2][4][2], const Unit& u, int wr, int wc, int fr, int fq) const {
;         const int row0 = u.pm * BM + wr * 64 + fr, col0 = u.pn * HALF + wc * 32 + 8 * fq;
;         const int s = (u.pm < ML / BM) ? (u.pm >> 5) : 4;
;         const float* bp = bias + (size_t)s * BIAS_N + u.pn * BM + wc * 32 + 8 * fq;
;         const f32x4 ba0 = *(const f32x4*)bp, ba1 = *(const f32x4*)(bp + 4), bb0 = *(const f32x4*)(bp + HALF), bb1 = *(const f32x4*)(bp + HALF + 4);
;         const int lane = fq * 16 + fr;
;         const float rsl0 = row_rstd(ss, u.pm * BM + wr * 64 + lane), rsl1 = row_rstd(ss, u.pm * BM + HALF + wr * 64 + lane);
; #pragma unroll
;         for (int ai = 0; ai < 2; ++ai)
; #pragma unroll
;             for (int m = 0; m < 4; ++m) { const int row = row0 + ai * HALF + m * 16; const float rs = __shfl(ai ? rsl1 : rsl0, m * 16 + fr); bf16_t* rowp = O + (size_t)row * DFF + col0;
;                 const f32x4 a0 = acc[ai][0][m][0] * rs + ba0, a1 = acc[ai][0][m][1] * rs + ba1, b0 = acc[ai][1][m][0] * rs + bb0, b1 = acc[ai][1][m][1] * rs + bb1;
;                 u32x4 w; w.x = cvt_pk_bf16(silu_mul(a0[0], b0[0]), silu_mul(a0[1], b0[1])); w.y = cvt_pk_bf16(silu_mul(a0[2], b0[2]), silu_mul(a0[3], b0[3]));
;                 w.z = cvt_pk_bf16(silu_mul(a1[0], b1[0]), silu_mul(a1[1], b1[1])); w.w = cvt_pk_bf16(silu_mul(a1[2], b1[2]), silu_mul(a1[3], b1[3]));
;                 *(u32x4*)rowp = w; }
.LBB0_193:
	s_lshl_b32 s2, s2, 8
	s_add_i32 s12, s2, s54
	s_lshl_b64 s[2:3], s[16:17], 2
	s_add_u32 s13, s68, s2
	s_addc_u32 s14, s69, s3
	s_lshl_b32 s2, s0, 8
	s_ashr_i32 s3, s2, 31
	s_lshl_b64 s[2:3], s[2:3], 2
	v_lshl_or_b32 v164, s0, 7, v173
	s_add_u32 s0, s13, s2
	s_addc_u32 s3, s14, s3
	v_or_b32_e32 v162, s12, v171
	s_add_u32 s2, s0, s60
	v_ashrrev_i32_e32 v163, 31, v162
	s_addc_u32 s3, s3, 0
	v_lshl_add_u64 v[162:163], v[162:163], 2, s[8:9]
	v_mov_b32_e32 v74, v234
	v_mov_b32_e32 v75, v235
	v_mov_b32_e32 v76, v236
	v_mov_b32_e32 v77, v237
	v_mov_b32_e32 v78, v238
	v_mov_b32_e32 v79, v239
	v_mov_b32_e32 v80, v240
	v_mov_b32_e32 v81, v241
	v_mov_b32_e32 v66, v242
	v_mov_b32_e32 v67, v243
	v_mov_b32_e32 v68, v244
	v_mov_b32_e32 v69, v245
	v_mov_b32_e32 v70, v246
	v_mov_b32_e32 v71, v247
	v_mov_b32_e32 v72, v248
	v_mov_b32_e32 v73, v249
	v_or_b32_e32 v181, s12, v169
	v_mov_b32_e32 v162, v250
	v_fmamk_f32 v162, v162, 0x3a000000, v178
	v_cmp_gt_f32_e32 vcc, s61, v162
	v_mul_f32_e32 v163, 0x4f800000, v162
	s_nop 0
	v_cndmask_b32_e32 v162, v162, v163, vcc
	v_sqrt_f32_e32 v163, v162
	s_nop 0
	v_add_u32_e32 v165, -1, v163
	v_fma_f32 v166, -v165, v163, v162
	v_cmp_ge_f32_e64 s[2:3], 0, v166
	v_add_u32_e32 v166, 1, v163
	s_nop 0
	v_cndmask_b32_e64 v165, v163, v165, s[2:3]
	v_fma_f32 v163, -v166, v163, v162
	v_cmp_lt_f32_e64 s[2:3], 0, v163
	s_nop 1
	v_cndmask_b32_e64 v163, v165, v166, s[2:3]
	v_mul_f32_e32 v165, 0x37800000, v163
	v_cndmask_b32_e32 v163, v163, v165, vcc
	v_cmp_class_f32_e32 vcc, v162, v179
	s_nop 1
	v_cndmask_b32_e32 v166, v163, v162, vcc
	v_add_u32_e32 v162, s12, v172
	v_ashrrev_i32_e32 v163, 31, v162
	v_lshl_add_u64 v[162:163], v[162:163], 2, s[8:9]
	v_mov_b32_e32 v162, v251
	v_fmamk_f32 v162, v162, 0x3a000000, v178
	v_cmp_gt_f32_e32 vcc, s61, v162
	v_mul_f32_e32 v163, 0x4f800000, v162
	s_nop 0
	v_cndmask_b32_e32 v162, v162, v163, vcc
	v_sqrt_f32_e32 v163, v162
	s_nop 0
	v_add_u32_e32 v165, -1, v163
	v_fma_f32 v167, -v165, v163, v162
	v_cmp_ge_f32_e64 s[2:3], 0, v167
	v_add_u32_e32 v167, 1, v163
	s_nop 0
	v_cndmask_b32_e64 v165, v163, v165, s[2:3]
	v_fma_f32 v163, -v167, v163, v162
	v_cmp_lt_f32_e64 s[2:3], 0, v163
	s_nop 1
	v_cndmask_b32_e64 v163, v165, v167, s[2:3]
	v_mul_f32_e32 v165, 0x37800000, v163
	v_cndmask_b32_e32 v163, v163, v165, vcc
	v_cmp_class_f32_e32 vcc, v162, v179
	v_ashrrev_i32_e32 v165, 31, v164
	v_lshlrev_b64 v[164:165], 1, v[164:165]
	v_cndmask_b32_e32 v182, v163, v162, vcc
	v_div_scale_f32 v162, s[2:3], v166, v166, 1.0
	v_rcp_f32_e32 v163, v162
	s_nop 0
	v_fma_f32 v167, -v162, v163, 1.0
	v_fmac_f32_e32 v163, v167, v163
	v_div_scale_f32 v167, vcc, 1.0, v166, 1.0
	v_mul_f32_e32 v168, v167, v163
	v_fma_f32 v183, -v162, v168, v167
	v_fmac_f32_e32 v168, v183, v163
	v_fma_f32 v162, -v162, v168, v167
	v_div_fmas_f32 v162, v162, v163, v168
	v_div_fixup_f32 v183, v162, v166, 1.0
	s_and_b64 vcc, exec, s[40:41]
	s_cbranch_vccz .Lalign_191
	s_barrier
.Lalign_191:
	s_mov_b32 s100, 0xbfb8aa3b
	ds_bpermute_b32 v242, v180, v183
	ds_bpermute_b32 v244, v180, v183 offset:64
	ds_bpermute_b32 v246, v180, v183 offset:128
	ds_bpermute_b32 v248, v180, v183 offset:192
	v_mov_b64_e32 v[162:163], s[96:97]
	v_mad_i64_i32 v[166:167], s[2:3], v181, s59, v[162:163]
	v_lshl_add_u64 v[166:167], v[166:167], 0, v[164:165]
	s_waitcnt lgkmcnt(0)
	v_pk_fma_f32 v[142:143], v[142:143], v[242:243], v[78:79] op_sel_hi:[1,0,1]
	v_pk_fma_f32 v[144:145], v[144:145], v[242:243], v[80:81] op_sel_hi:[1,0,1]
	v_pk_fma_f32 v[134:135], v[134:135], v[242:243], v[70:71] op_sel_hi:[1,0,1]
	v_pk_fma_f32 v[136:137], v[136:137], v[242:243], v[72:73] op_sel_hi:[1,0,1]
	v_pk_fma_f32 v[138:139], v[138:139], v[242:243], v[74:75] op_sel_hi:[1,0,1]
	v_pk_fma_f32 v[140:141], v[140:141], v[242:243], v[76:77] op_sel_hi:[1,0,1]
	v_pk_fma_f32 v[130:131], v[130:131], v[242:243], v[66:67] op_sel_hi:[1,0,1]
	v_pk_fma_f32 v[132:133], v[132:133], v[242:243], v[68:69] op_sel_hi:[1,0,1]
	v_pk_mul_f32 v[234:235], v[142:143], s[100:101] op_sel_hi:[1,0]
	v_pk_mul_f32 v[236:237], v[144:145], s[100:101] op_sel_hi:[1,0]
	v_exp_f32_e32 v234, v234
	v_exp_f32_e32 v235, v235
	v_exp_f32_e32 v236, v236
	v_exp_f32_e32 v237, v237
	v_pk_add_f32 v[234:235], v[234:235], 1.0 op_sel_hi:[1,0]
	v_pk_add_f32 v[236:237], v[236:237], 1.0 op_sel_hi:[1,0]
	v_rcp_f32_e32 v234, v234
	v_rcp_f32_e32 v235, v235
	v_rcp_f32_e32 v236, v236
	v_rcp_f32_e32 v237, v237
	v_pk_mul_f32 v[134:135], v[142:143], v[134:135]
	v_pk_mul_f32 v[136:137], v[144:145], v[136:137]
	v_pk_mul_f32 v[134:135], v[134:135], v[234:235]
	v_pk_mul_f32 v[136:137], v[136:137], v[236:237]
	v_cvt_pk_bf16_f32 v238, v134, v135
	v_cvt_pk_bf16_f32 v239, v136, v137
	v_pk_mul_f32 v[234:235], v[138:139], s[100:101] op_sel_hi:[1,0]
	v_pk_mul_f32 v[236:237], v[140:141], s[100:101] op_sel_hi:[1,0]
	v_exp_f32_e32 v234, v234
	v_exp_f32_e32 v235, v235
	v_exp_f32_e32 v236, v236
	v_exp_f32_e32 v237, v237
	v_pk_add_f32 v[234:235], v[234:235], 1.0 op_sel_hi:[1,0]
	v_pk_add_f32 v[236:237], v[236:237], 1.0 op_sel_hi:[1,0]
	v_rcp_f32_e32 v234, v234
	v_rcp_f32_e32 v235, v235
	v_rcp_f32_e32 v236, v236
	v_rcp_f32_e32 v237, v237
	v_pk_mul_f32 v[130:131], v[138:139], v[130:131]
	v_pk_mul_f32 v[132:133], v[140:141], v[132:133]
	v_pk_mul_f32 v[130:131], v[130:131], v[234:235]
	v_pk_mul_f32 v[132:133], v[132:133], v[236:237]
	v_cvt_pk_bf16_f32 v240, v130, v131
	v_cvt_pk_bf16_f32 v241, v132, v133
	global_store_dwordx4 v[166:167], v[238:241], off
	v_or_b32_e32 v131, 16, v181
	v_mad_i64_i32 v[132:133], s[2:3], v131, s59, v[162:163]
	v_lshl_add_u64 v[132:133], v[132:133], 0, v[164:165]
	v_pk_fma_f32 v[126:127], v[126:127], v[244:245], v[78:79] op_sel_hi:[1,0,1]
; __device__ __forceinline__ unsigned cvt_pk_bf16(float lo, float hi) { unsigned r; asm volatile("v_cvt_pk_bf16_f32 %0, %1, %2" : "=v"(r) : "v"(lo), "v"(hi)); return r; }
; __device__ __forceinline__ float silu_mul(float a, float b) { return a * b * __builtin_amdgcn_rcpf(1.0f + __builtin_amdgcn_exp2f(-a * LOG2E)); }
;     __device__ __forceinline__ void operator()(const f32x4 (&acc)[2][2][4][2], const Unit& u, int wr, int wc, int fr, int fq) const {
;     ...
;             for (int m = 0; m < 4; ++m) { const int row = row0 + ai * HALF + m * 16; const float rs = __shfl(ai ? rsl1 : rsl0, m * 16 + fr); bf16_t* rowp = O + (size_t)row * DFF + col0;
;                 const f32x4 a0 = acc[ai][0][m][0] * rs + ba0, a1 = acc[ai][0][m][1] * rs + ba1, b0 = acc[ai][1][m][0] * rs + bb0, b1 = acc[ai][1][m][1] * rs + bb1;
;                 u32x4 w; w.x = cvt_pk_bf16(silu_mul(a0[0], b0[0]), silu_mul(a0[1], b0[1])); w.y = cvt_pk_bf16(silu_mul(a0[2], b0[2]), silu_mul(a0[3], b0[3]));
;                 w.z = cvt_pk_bf16(silu_mul(a1[0], b1[0]), silu_mul(a1[1], b1[1])); w.w = cvt_pk_bf16(silu_mul(a1[2], b1[2]), silu_mul(a1[3], b1[3]));
;                 *(u32x4*)rowp = w; }
	v_pk_fma_f32 v[128:129], v[128:129], v[244:245], v[80:81] op_sel_hi:[1,0,1]
	v_pk_fma_f32 v[118:119], v[118:119], v[244:245], v[70:71] op_sel_hi:[1,0,1]
	v_pk_fma_f32 v[120:121], v[120:121], v[244:245], v[72:73] op_sel_hi:[1,0,1]
	v_pk_fma_f32 v[122:123], v[122:123], v[244:245], v[74:75] op_sel_hi:[1,0,1]
	v_pk_fma_f32 v[124:125], v[124:125], v[244:245], v[76:77] op_sel_hi:[1,0,1]
	v_pk_fma_f32 v[114:115], v[114:115], v[244:245], v[66:67] op_sel_hi:[1,0,1]
	v_pk_fma_f32 v[116:117], v[116:117], v[244:245], v[68:69] op_sel_hi:[1,0,1]
	v_pk_mul_f32 v[234:235], v[126:127], s[100:101] op_sel_hi:[1,0]
	v_pk_mul_f32 v[236:237], v[128:129], s[100:101] op_sel_hi:[1,0]
	v_exp_f32_e32 v234, v234
	v_exp_f32_e32 v235, v235
	v_exp_f32_e32 v236, v236
	v_exp_f32_e32 v237, v237
	v_pk_add_f32 v[234:235], v[234:235], 1.0 op_sel_hi:[1,0]
	v_pk_add_f32 v[236:237], v[236:237], 1.0 op_sel_hi:[1,0]
	v_rcp_f32_e32 v234, v234
	v_rcp_f32_e32 v235, v235
	v_rcp_f32_e32 v236, v236
	v_rcp_f32_e32 v237, v237
	v_pk_mul_f32 v[118:119], v[126:127], v[118:119]
	v_pk_mul_f32 v[120:121], v[128:129], v[120:121]
	v_pk_mul_f32 v[118:119], v[118:119], v[234:235]
	v_pk_mul_f32 v[120:121], v[120:121], v[236:237]
	v_cvt_pk_bf16_f32 v238, v118, v119
	v_cvt_pk_bf16_f32 v239, v120, v121
	v_pk_mul_f32 v[234:235], v[122:123], s[100:101] op_sel_hi:[1,0]
	v_pk_mul_f32 v[236:237], v[124:125], s[100:101] op_sel_hi:[1,0]
	v_exp_f32_e32 v234, v234
	v_exp_f32_e32 v235, v235
	v_exp_f32_e32 v236, v236
	v_exp_f32_e32 v237, v237
	v_pk_add_f32 v[234:235], v[234:235], 1.0 op_sel_hi:[1,0]
	v_pk_add_f32 v[236:237], v[236:237], 1.0 op_sel_hi:[1,0]
	v_rcp_f32_e32 v234, v234
	v_rcp_f32_e32 v235, v235
	v_rcp_f32_e32 v236, v236
	v_rcp_f32_e32 v237, v237
	v_pk_mul_f32 v[114:115], v[122:123], v[114:115]
	v_pk_mul_f32 v[116:117], v[124:125], v[116:117]
	v_pk_mul_f32 v[114:115], v[114:115], v[234:235]
	v_pk_mul_f32 v[116:117], v[116:117], v[236:237]
	v_cvt_pk_bf16_f32 v240, v114, v115
	v_cvt_pk_bf16_f32 v241, v116, v117
	global_store_dwordx4 v[132:133], v[238:241], off
	v_or_b32_e32 v115, 32, v181
	v_mad_i64_i32 v[116:117], s[2:3], v115, s59, v[162:163]
	v_lshl_add_u64 v[116:117], v[116:117], 0, v[164:165]
	v_pk_fma_f32 v[110:111], v[110:111], v[246:247], v[78:79] op_sel_hi:[1,0,1]
	v_pk_fma_f32 v[112:113], v[112:113], v[246:247], v[80:81] op_sel_hi:[1,0,1]
	v_pk_fma_f32 v[102:103], v[102:103], v[246:247], v[70:71] op_sel_hi:[1,0,1]
	v_pk_fma_f32 v[104:105], v[104:105], v[246:247], v[72:73] op_sel_hi:[1,0,1]
	v_pk_fma_f32 v[106:107], v[106:107], v[246:247], v[74:75] op_sel_hi:[1,0,1]
	v_pk_fma_f32 v[108:109], v[108:109], v[246:247], v[76:77] op_sel_hi:[1,0,1]
	v_pk_fma_f32 v[98:99], v[98:99], v[246:247], v[66:67] op_sel_hi:[1,0,1]
	v_pk_fma_f32 v[100:101], v[100:101], v[246:247], v[68:69] op_sel_hi:[1,0,1]
	v_pk_mul_f32 v[234:235], v[110:111], s[100:101] op_sel_hi:[1,0]
	v_pk_mul_f32 v[236:237], v[112:113], s[100:101] op_sel_hi:[1,0]
	v_exp_f32_e32 v234, v234
	v_exp_f32_e32 v235, v235
	v_exp_f32_e32 v236, v236
	v_exp_f32_e32 v237, v237
	v_pk_add_f32 v[234:235], v[234:235], 1.0 op_sel_hi:[1,0]
	v_pk_add_f32 v[236:237], v[236:237], 1.0 op_sel_hi:[1,0]
	v_rcp_f32_e32 v234, v234
	v_rcp_f32_e32 v235, v235
	v_rcp_f32_e32 v236, v236
	v_rcp_f32_e32 v237, v237
	v_pk_mul_f32 v[102:103], v[110:111], v[102:103]
	v_pk_mul_f32 v[104:105], v[112:113], v[104:105]
	v_pk_mul_f32 v[102:103], v[102:103], v[234:235]
	v_pk_mul_f32 v[104:105], v[104:105], v[236:237]
	v_cvt_pk_bf16_f32 v238, v102, v103
	v_cvt_pk_bf16_f32 v239, v104, v105
	v_pk_mul_f32 v[234:235], v[106:107], s[100:101] op_sel_hi:[1,0]
	v_pk_mul_f32 v[236:237], v[108:109], s[100:101] op_sel_hi:[1,0]
	v_exp_f32_e32 v234, v234
	v_exp_f32_e32 v235, v235
	v_exp_f32_e32 v236, v236
	v_exp_f32_e32 v237, v237
	v_pk_add_f32 v[234:235], v[234:235], 1.0 op_sel_hi:[1,0]
	v_pk_add_f32 v[236:237], v[236:237], 1.0 op_sel_hi:[1,0]
	v_rcp_f32_e32 v234, v234
	v_rcp_f32_e32 v235, v235
	v_rcp_f32_e32 v236, v236
	v_rcp_f32_e32 v237, v237
	v_pk_mul_f32 v[98:99], v[106:107], v[98:99]
	v_pk_mul_f32 v[100:101], v[108:109], v[100:101]
	v_pk_mul_f32 v[98:99], v[98:99], v[234:235]
	v_pk_mul_f32 v[100:101], v[100:101], v[236:237]
	v_cvt_pk_bf16_f32 v240, v98, v99
	v_cvt_pk_bf16_f32 v241, v100, v101
	global_store_dwordx4 v[116:117], v[238:241], off
	v_or_b32_e32 v99, 48, v181
	v_mad_i64_i32 v[100:101], s[2:3], v99, s59, v[162:163]
	v_lshl_add_u64 v[100:101], v[100:101], 0, v[164:165]
	v_pk_fma_f32 v[94:95], v[94:95], v[248:249], v[78:79] op_sel_hi:[1,0,1]
	v_pk_fma_f32 v[96:97], v[96:97], v[248:249], v[80:81] op_sel_hi:[1,0,1]
	v_pk_fma_f32 v[86:87], v[86:87], v[248:249], v[70:71] op_sel_hi:[1,0,1]
	v_pk_fma_f32 v[88:89], v[88:89], v[248:249], v[72:73] op_sel_hi:[1,0,1]
	v_pk_fma_f32 v[90:91], v[90:91], v[248:249], v[74:75] op_sel_hi:[1,0,1]
	v_pk_fma_f32 v[92:93], v[92:93], v[248:249], v[76:77] op_sel_hi:[1,0,1]
	v_pk_fma_f32 v[82:83], v[82:83], v[248:249], v[66:67] op_sel_hi:[1,0,1]
	v_pk_fma_f32 v[84:85], v[84:85], v[248:249], v[68:69] op_sel_hi:[1,0,1]
	v_pk_mul_f32 v[234:235], v[94:95], s[100:101] op_sel_hi:[1,0]
	v_pk_mul_f32 v[236:237], v[96:97], s[100:101] op_sel_hi:[1,0]
	v_exp_f32_e32 v234, v234
	v_exp_f32_e32 v235, v235
	v_exp_f32_e32 v236, v236
	v_exp_f32_e32 v237, v237
	v_pk_add_f32 v[234:235], v[234:235], 1.0 op_sel_hi:[1,0]
	v_pk_add_f32 v[236:237], v[236:237], 1.0 op_sel_hi:[1,0]
	v_rcp_f32_e32 v234, v234
	v_rcp_f32_e32 v235, v235
	v_rcp_f32_e32 v236, v236
	v_rcp_f32_e32 v237, v237
	v_pk_mul_f32 v[86:87], v[94:95], v[86:87]
	v_pk_mul_f32 v[88:89], v[96:97], v[88:89]
	v_pk_mul_f32 v[86:87], v[86:87], v[234:235]
	v_pk_mul_f32 v[88:89], v[88:89], v[236:237]
	v_cvt_pk_bf16_f32 v238, v86, v87
; __device__ __forceinline__ unsigned cvt_pk_bf16(float lo, float hi) { unsigned r; asm volatile("v_cvt_pk_bf16_f32 %0, %1, %2" : "=v"(r) : "v"(lo), "v"(hi)); return r; }
; __device__ __forceinline__ float row_rstd(const float* ss, int row) { return 1.0f / sqrtf(ss[row] * (1.0f / DM) + 1e-6f); }
; __device__ __forceinline__ float silu_mul(float a, float b) { return a * b * __builtin_amdgcn_rcpf(1.0f + __builtin_amdgcn_exp2f(-a * LOG2E)); }
;     __device__ __forceinline__ void operator()(const f32x4 (&acc)[2][2][4][2], const Unit& u, int wr, int wc, int fr, int fq) const {
;     ...
;         const float rsl0 = row_rstd(ss, u.pm * BM + wr * 64 + lane), rsl1 = row_rstd(ss, u.pm * BM + HALF + wr * 64 + lane);
; #pragma unroll
;         for (int ai = 0; ai < 2; ++ai)
; #pragma unroll
;             for (int m = 0; m < 4; ++m) { const int row = row0 + ai * HALF + m * 16; const float rs = __shfl(ai ? rsl1 : rsl0, m * 16 + fr); bf16_t* rowp = O + (size_t)row * DFF + col0;
;                 const f32x4 a0 = acc[ai][0][m][0] * rs + ba0, a1 = acc[ai][0][m][1] * rs + ba1, b0 = acc[ai][1][m][0] * rs + bb0, b1 = acc[ai][1][m][1] * rs + bb1;
;                 u32x4 w; w.x = cvt_pk_bf16(silu_mul(a0[0], b0[0]), silu_mul(a0[1], b0[1])); w.y = cvt_pk_bf16(silu_mul(a0[2], b0[2]), silu_mul(a0[3], b0[3]));
;                 w.z = cvt_pk_bf16(silu_mul(a1[0], b1[0]), silu_mul(a1[1], b1[1])); w.w = cvt_pk_bf16(silu_mul(a1[2], b1[2]), silu_mul(a1[3], b1[3]));
;                 *(u32x4*)rowp = w; }
	v_cvt_pk_bf16_f32 v239, v88, v89
	v_pk_mul_f32 v[234:235], v[90:91], s[100:101] op_sel_hi:[1,0]
	v_pk_mul_f32 v[236:237], v[92:93], s[100:101] op_sel_hi:[1,0]
	v_exp_f32_e32 v234, v234
	v_exp_f32_e32 v235, v235
	v_exp_f32_e32 v236, v236
	v_exp_f32_e32 v237, v237
	v_pk_add_f32 v[234:235], v[234:235], 1.0 op_sel_hi:[1,0]
	v_pk_add_f32 v[236:237], v[236:237], 1.0 op_sel_hi:[1,0]
	v_rcp_f32_e32 v234, v234
	v_rcp_f32_e32 v235, v235
	v_rcp_f32_e32 v236, v236
	v_rcp_f32_e32 v237, v237
	v_pk_mul_f32 v[82:83], v[90:91], v[82:83]
	v_pk_mul_f32 v[84:85], v[92:93], v[84:85]
	v_pk_mul_f32 v[82:83], v[82:83], v[234:235]
	v_pk_mul_f32 v[84:85], v[84:85], v[236:237]
	v_cvt_pk_bf16_f32 v240, v82, v83
	v_cvt_pk_bf16_f32 v241, v84, v85
	global_store_dwordx4 v[100:101], v[238:241], off
	s_nop 1
	v_div_scale_f32 v82, s[2:3], v182, v182, 1.0
	v_rcp_f32_e32 v84, v82
	v_add_u32_e32 v83, 0x80, v181
	v_fma_f32 v85, -v82, v84, 1.0
	v_fmac_f32_e32 v84, v85, v84
	v_div_scale_f32 v85, vcc, 1.0, v182, 1.0
	v_mul_f32_e32 v86, v85, v84
	v_fma_f32 v87, -v82, v86, v85
	v_fmac_f32_e32 v86, v87, v84
	v_fma_f32 v82, -v82, v86, v85
	v_div_fmas_f32 v82, v82, v84, v86
	v_div_fixup_f32 v82, v82, v182, 1.0
	ds_bpermute_b32 v242, v180, v82
	ds_bpermute_b32 v244, v180, v82 offset:64
	ds_bpermute_b32 v246, v180, v82 offset:128
	ds_bpermute_b32 v248, v180, v82 offset:192
	v_mad_i64_i32 v[86:87], s[2:3], v83, s59, v[162:163]
	v_lshl_add_u64 v[86:87], v[86:87], 0, v[164:165]
	s_andn2_b64 vcc, exec, s[38:39]
	s_waitcnt lgkmcnt(0)
	v_pk_fma_f32 v[62:63], v[62:63], v[242:243], v[78:79] op_sel_hi:[1,0,1]
	v_pk_fma_f32 v[64:65], v[64:65], v[242:243], v[80:81] op_sel_hi:[1,0,1]
	v_pk_fma_f32 v[54:55], v[54:55], v[242:243], v[70:71] op_sel_hi:[1,0,1]
	v_pk_fma_f32 v[56:57], v[56:57], v[242:243], v[72:73] op_sel_hi:[1,0,1]
	v_pk_fma_f32 v[58:59], v[58:59], v[242:243], v[74:75] op_sel_hi:[1,0,1]
	v_pk_fma_f32 v[60:61], v[60:61], v[242:243], v[76:77] op_sel_hi:[1,0,1]
	v_pk_fma_f32 v[50:51], v[50:51], v[242:243], v[66:67] op_sel_hi:[1,0,1]
	v_pk_fma_f32 v[52:53], v[52:53], v[242:243], v[68:69] op_sel_hi:[1,0,1]
	v_pk_mul_f32 v[234:235], v[62:63], s[100:101] op_sel_hi:[1,0]
	v_pk_mul_f32 v[236:237], v[64:65], s[100:101] op_sel_hi:[1,0]
	v_exp_f32_e32 v234, v234
	v_exp_f32_e32 v235, v235
	v_exp_f32_e32 v236, v236
	v_exp_f32_e32 v237, v237
	v_pk_add_f32 v[234:235], v[234:235], 1.0 op_sel_hi:[1,0]
	v_pk_add_f32 v[236:237], v[236:237], 1.0 op_sel_hi:[1,0]
	v_rcp_f32_e32 v234, v234
	v_rcp_f32_e32 v235, v235
	v_rcp_f32_e32 v236, v236
	v_rcp_f32_e32 v237, v237
	v_pk_mul_f32 v[54:55], v[62:63], v[54:55]
	v_pk_mul_f32 v[56:57], v[64:65], v[56:57]
	v_pk_mul_f32 v[54:55], v[54:55], v[234:235]
	v_pk_mul_f32 v[56:57], v[56:57], v[236:237]
	v_cvt_pk_bf16_f32 v238, v54, v55
	v_cvt_pk_bf16_f32 v239, v56, v57
	v_pk_mul_f32 v[234:235], v[58:59], s[100:101] op_sel_hi:[1,0]
	v_pk_mul_f32 v[236:237], v[60:61], s[100:101] op_sel_hi:[1,0]
	v_exp_f32_e32 v234, v234
	v_exp_f32_e32 v235, v235
	v_exp_f32_e32 v236, v236
	v_exp_f32_e32 v237, v237
	v_pk_add_f32 v[234:235], v[234:235], 1.0 op_sel_hi:[1,0]
	v_pk_add_f32 v[236:237], v[236:237], 1.0 op_sel_hi:[1,0]
	v_rcp_f32_e32 v234, v234
	v_rcp_f32_e32 v235, v235
	v_rcp_f32_e32 v236, v236
	v_rcp_f32_e32 v237, v237
	v_pk_mul_f32 v[50:51], v[58:59], v[50:51]
	v_pk_mul_f32 v[52:53], v[60:61], v[52:53]
	v_pk_mul_f32 v[50:51], v[50:51], v[234:235]
	v_pk_mul_f32 v[52:53], v[52:53], v[236:237]
	v_cvt_pk_bf16_f32 v240, v50, v51
	v_cvt_pk_bf16_f32 v241, v52, v53
	global_store_dwordx4 v[86:87], v[238:241], off
	v_add_u32_e32 v51, 0x90, v181
	v_mad_i64_i32 v[52:53], s[2:3], v51, s59, v[162:163]
	v_lshl_add_u64 v[52:53], v[52:53], 0, v[164:165]
	v_pk_fma_f32 v[46:47], v[46:47], v[244:245], v[78:79] op_sel_hi:[1,0,1]
	v_pk_fma_f32 v[48:49], v[48:49], v[244:245], v[80:81] op_sel_hi:[1,0,1]
	v_pk_fma_f32 v[38:39], v[38:39], v[244:245], v[70:71] op_sel_hi:[1,0,1]
	v_pk_fma_f32 v[40:41], v[40:41], v[244:245], v[72:73] op_sel_hi:[1,0,1]
	v_pk_fma_f32 v[42:43], v[42:43], v[244:245], v[74:75] op_sel_hi:[1,0,1]
	v_pk_fma_f32 v[44:45], v[44:45], v[244:245], v[76:77] op_sel_hi:[1,0,1]
	v_pk_fma_f32 v[34:35], v[34:35], v[244:245], v[66:67] op_sel_hi:[1,0,1]
	v_pk_fma_f32 v[36:37], v[36:37], v[244:245], v[68:69] op_sel_hi:[1,0,1]
	v_pk_mul_f32 v[234:235], v[46:47], s[100:101] op_sel_hi:[1,0]
	v_pk_mul_f32 v[236:237], v[48:49], s[100:101] op_sel_hi:[1,0]
	v_exp_f32_e32 v234, v234
	v_exp_f32_e32 v235, v235
	v_exp_f32_e32 v236, v236
	v_exp_f32_e32 v237, v237
	v_pk_add_f32 v[234:235], v[234:235], 1.0 op_sel_hi:[1,0]
	v_pk_add_f32 v[236:237], v[236:237], 1.0 op_sel_hi:[1,0]
	v_rcp_f32_e32 v234, v234
	v_rcp_f32_e32 v235, v235
	v_rcp_f32_e32 v236, v236
	v_rcp_f32_e32 v237, v237
	v_pk_mul_f32 v[38:39], v[46:47], v[38:39]
	v_pk_mul_f32 v[40:41], v[48:49], v[40:41]
	v_pk_mul_f32 v[38:39], v[38:39], v[234:235]
	v_pk_mul_f32 v[40:41], v[40:41], v[236:237]
	v_cvt_pk_bf16_f32 v238, v38, v39
	v_cvt_pk_bf16_f32 v239, v40, v41
	v_pk_mul_f32 v[234:235], v[42:43], s[100:101] op_sel_hi:[1,0]
	v_pk_mul_f32 v[236:237], v[44:45], s[100:101] op_sel_hi:[1,0]
; __device__ __forceinline__ unsigned cvt_pk_bf16(float lo, float hi) { unsigned r; asm volatile("v_cvt_pk_bf16_f32 %0, %1, %2" : "=v"(r) : "v"(lo), "v"(hi)); return r; }
; __device__ __forceinline__ float silu_mul(float a, float b) { return a * b * __builtin_amdgcn_rcpf(1.0f + __builtin_amdgcn_exp2f(-a * LOG2E)); }
; #define PG8_BAR __builtin_amdgcn_s_barrier()
;     __device__ __forceinline__ void operator()(const f32x4 (&acc)[2][2][4][2], const Unit& u, int wr, int wc, int fr, int fq) const {
;     ...
;             for (int m = 0; m < 4; ++m) { const int row = row0 + ai * HALF + m * 16; const float rs = __shfl(ai ? rsl1 : rsl0, m * 16 + fr); bf16_t* rowp = O + (size_t)row * DFF + col0;
;                 const f32x4 a0 = acc[ai][0][m][0] * rs + ba0, a1 = acc[ai][0][m][1] * rs + ba1, b0 = acc[ai][1][m][0] * rs + bb0, b1 = acc[ai][1][m][1] * rs + bb1;
;                 u32x4 w; w.x = cvt_pk_bf16(silu_mul(a0[0], b0[0]), silu_mul(a0[1], b0[1])); w.y = cvt_pk_bf16(silu_mul(a0[2], b0[2]), silu_mul(a0[3], b0[3]));
;                 w.z = cvt_pk_bf16(silu_mul(a1[0], b1[0]), silu_mul(a1[1], b1[1])); w.w = cvt_pk_bf16(silu_mul(a1[2], b1[2]), silu_mul(a1[3], b1[3]));
;                 *(u32x4*)rowp = w; }
; template <class Epi, class Sched, bool ALIGN_EPI = false, bool SP2 = false>
; __device__ __forceinline__ void gemm_phase(LAS unsigned char* lds, const Gemm g, const Sched& S, const Epi& E) {
;     ...
;         if constexpr (!Epi::AFTER_DRAIN) { E(acc, cur, wr, wc, fr, fq); S.done(cur); }
;         if (!has_next) break;
; #pragma unroll
;         for (int a = 0; a < 2; ++a)
; #pragma unroll
;             for (int b = 0; b < 2; ++b)
; #pragma unroll
;                 for (int m = 0; m < 4; ++m)
; #pragma unroll
;                     for (int n = 0; n < 2; ++n) acc[a][b][m][n] = (f32x4){0.f, 0.f, 0.f, 0.f};
;         cur = nxt; cA = nA; cB = nB; ++ui;
;         if constexpr (ALIGN_EPI) { if (wr == 1) PG8_BAR; }
	v_exp_f32_e32 v234, v234
	v_exp_f32_e32 v235, v235
	v_exp_f32_e32 v236, v236
	v_exp_f32_e32 v237, v237
	v_pk_add_f32 v[234:235], v[234:235], 1.0 op_sel_hi:[1,0]
	v_pk_add_f32 v[236:237], v[236:237], 1.0 op_sel_hi:[1,0]
	v_rcp_f32_e32 v234, v234
	v_rcp_f32_e32 v235, v235
	v_rcp_f32_e32 v236, v236
	v_rcp_f32_e32 v237, v237
	v_pk_mul_f32 v[34:35], v[42:43], v[34:35]
	v_pk_mul_f32 v[36:37], v[44:45], v[36:37]
	v_pk_mul_f32 v[34:35], v[34:35], v[234:235]
	v_pk_mul_f32 v[36:37], v[36:37], v[236:237]
	v_cvt_pk_bf16_f32 v240, v34, v35
	v_cvt_pk_bf16_f32 v241, v36, v37
	global_store_dwordx4 v[52:53], v[238:241], off
	v_add_u32_e32 v35, 0xa0, v181
	v_mad_i64_i32 v[36:37], s[2:3], v35, s59, v[162:163]
	v_lshl_add_u64 v[36:37], v[36:37], 0, v[164:165]
	v_pk_fma_f32 v[30:31], v[30:31], v[246:247], v[78:79] op_sel_hi:[1,0,1]
	v_pk_fma_f32 v[32:33], v[32:33], v[246:247], v[80:81] op_sel_hi:[1,0,1]
	v_pk_fma_f32 v[22:23], v[22:23], v[246:247], v[70:71] op_sel_hi:[1,0,1]
	v_pk_fma_f32 v[24:25], v[24:25], v[246:247], v[72:73] op_sel_hi:[1,0,1]
	v_pk_fma_f32 v[26:27], v[26:27], v[246:247], v[74:75] op_sel_hi:[1,0,1]
	v_pk_fma_f32 v[28:29], v[28:29], v[246:247], v[76:77] op_sel_hi:[1,0,1]
	v_pk_fma_f32 v[18:19], v[18:19], v[246:247], v[66:67] op_sel_hi:[1,0,1]
	v_pk_fma_f32 v[20:21], v[20:21], v[246:247], v[68:69] op_sel_hi:[1,0,1]
	v_pk_mul_f32 v[234:235], v[30:31], s[100:101] op_sel_hi:[1,0]
	v_pk_mul_f32 v[236:237], v[32:33], s[100:101] op_sel_hi:[1,0]
	v_exp_f32_e32 v234, v234
	v_exp_f32_e32 v235, v235
	v_exp_f32_e32 v236, v236
	v_exp_f32_e32 v237, v237
	v_pk_add_f32 v[234:235], v[234:235], 1.0 op_sel_hi:[1,0]
	v_pk_add_f32 v[236:237], v[236:237], 1.0 op_sel_hi:[1,0]
	v_rcp_f32_e32 v234, v234
	v_rcp_f32_e32 v235, v235
	v_rcp_f32_e32 v236, v236
	v_rcp_f32_e32 v237, v237
	v_pk_mul_f32 v[22:23], v[30:31], v[22:23]
	v_pk_mul_f32 v[24:25], v[32:33], v[24:25]
	v_pk_mul_f32 v[22:23], v[22:23], v[234:235]
	v_pk_mul_f32 v[24:25], v[24:25], v[236:237]
	v_cvt_pk_bf16_f32 v238, v22, v23
	v_cvt_pk_bf16_f32 v239, v24, v25
	v_pk_mul_f32 v[234:235], v[26:27], s[100:101] op_sel_hi:[1,0]
	v_pk_mul_f32 v[236:237], v[28:29], s[100:101] op_sel_hi:[1,0]
	v_exp_f32_e32 v234, v234
	v_exp_f32_e32 v235, v235
	v_exp_f32_e32 v236, v236
	v_exp_f32_e32 v237, v237
	v_pk_add_f32 v[234:235], v[234:235], 1.0 op_sel_hi:[1,0]
	v_pk_add_f32 v[236:237], v[236:237], 1.0 op_sel_hi:[1,0]
	v_rcp_f32_e32 v234, v234
	v_rcp_f32_e32 v235, v235
	v_rcp_f32_e32 v236, v236
	v_rcp_f32_e32 v237, v237
	v_pk_mul_f32 v[18:19], v[26:27], v[18:19]
	v_pk_mul_f32 v[20:21], v[28:29], v[20:21]
	v_pk_mul_f32 v[18:19], v[18:19], v[234:235]
	v_pk_mul_f32 v[20:21], v[20:21], v[236:237]
	v_cvt_pk_bf16_f32 v240, v18, v19
	v_cvt_pk_bf16_f32 v241, v20, v21
	global_store_dwordx4 v[36:37], v[238:241], off
	v_add_u32_e32 v19, 0xb0, v181
	v_mad_i64_i32 v[20:21], s[2:3], v19, s59, v[162:163]
	v_lshl_add_u64 v[20:21], v[20:21], 0, v[164:165]
	s_mov_b64 s[2:3], -1
	v_pk_fma_f32 v[14:15], v[14:15], v[248:249], v[78:79] op_sel_hi:[1,0,1]
	v_pk_fma_f32 v[16:17], v[16:17], v[248:249], v[80:81] op_sel_hi:[1,0,1]
	v_pk_fma_f32 v[6:7], v[6:7], v[248:249], v[70:71] op_sel_hi:[1,0,1]
	v_pk_fma_f32 v[8:9], v[8:9], v[248:249], v[72:73] op_sel_hi:[1,0,1]
	v_pk_fma_f32 v[10:11], v[10:11], v[248:249], v[74:75] op_sel_hi:[1,0,1]
	v_pk_fma_f32 v[12:13], v[12:13], v[248:249], v[76:77] op_sel_hi:[1,0,1]
	v_pk_fma_f32 v[2:3], v[2:3], v[248:249], v[66:67] op_sel_hi:[1,0,1]
	v_pk_fma_f32 v[4:5], v[4:5], v[248:249], v[68:69] op_sel_hi:[1,0,1]
	v_pk_mul_f32 v[234:235], v[14:15], s[100:101] op_sel_hi:[1,0]
	v_pk_mul_f32 v[236:237], v[16:17], s[100:101] op_sel_hi:[1,0]
	v_exp_f32_e32 v234, v234
	v_exp_f32_e32 v235, v235
	v_exp_f32_e32 v236, v236
	v_exp_f32_e32 v237, v237
	v_pk_add_f32 v[234:235], v[234:235], 1.0 op_sel_hi:[1,0]
	v_pk_add_f32 v[236:237], v[236:237], 1.0 op_sel_hi:[1,0]
	v_rcp_f32_e32 v234, v234
	v_rcp_f32_e32 v235, v235
	v_rcp_f32_e32 v236, v236
	v_rcp_f32_e32 v237, v237
	v_pk_mul_f32 v[6:7], v[14:15], v[6:7]
	v_pk_mul_f32 v[8:9], v[16:17], v[8:9]
	v_pk_mul_f32 v[6:7], v[6:7], v[234:235]
	v_pk_mul_f32 v[8:9], v[8:9], v[236:237]
	v_cvt_pk_bf16_f32 v238, v6, v7
	v_cvt_pk_bf16_f32 v239, v8, v9
	v_pk_mul_f32 v[234:235], v[10:11], s[100:101] op_sel_hi:[1,0]
	v_pk_mul_f32 v[236:237], v[12:13], s[100:101] op_sel_hi:[1,0]
	v_exp_f32_e32 v234, v234
	v_exp_f32_e32 v235, v235
	v_exp_f32_e32 v236, v236
	v_exp_f32_e32 v237, v237
	v_pk_add_f32 v[234:235], v[234:235], 1.0 op_sel_hi:[1,0]
	v_pk_add_f32 v[236:237], v[236:237], 1.0 op_sel_hi:[1,0]
	v_rcp_f32_e32 v234, v234
	v_rcp_f32_e32 v235, v235
	v_rcp_f32_e32 v236, v236
	v_rcp_f32_e32 v237, v237
	v_pk_mul_f32 v[2:3], v[10:11], v[2:3]
	v_pk_mul_f32 v[4:5], v[12:13], v[4:5]
	v_pk_mul_f32 v[2:3], v[2:3], v[234:235]
	v_pk_mul_f32 v[4:5], v[4:5], v[236:237]
	v_cvt_pk_bf16_f32 v240, v2, v3
	v_cvt_pk_bf16_f32 v241, v4, v5
	global_store_dwordx4 v[20:21], v[238:241], off
	s_waitcnt vmcnt(8)
	s_cbranch_vccnz .LBB0_184
	s_andn2_b64 vcc, exec, s[4:5]
	s_cbranch_vccnz .LBB0_183
	s_barrier
	s_branch .LBB0_183

; __device__ __forceinline__ unsigned cvt_pk_bf16(float lo, float hi) { unsigned r; asm volatile("v_cvt_pk_bf16_f32 %0, %1, %2" : "=v"(r) : "v"(lo), "v"(hi)); return r; }
; __device__ __forceinline__ float silu_mul(float a, float b) { return a * b * __builtin_amdgcn_rcpf(1.0f + __builtin_amdgcn_exp2f(-a * LOG2E)); }
; __device__ __forceinline__ float row_rstd(const float* ss, int row) { return 1.0f / sqrtf(ss[row] * (1.0f / DM) + 1e-6f); }
;     __device__ __forceinline__ void operator()(const f32x4 (&acc)[2][2][4][2], const Unit& u, int wr, int wc, int fr, int fq) const {
;         const int row0 = u.pm * BM + wr * 64 + fr, col0 = u.pn * HALF + wc * 32 + 8 * fq;
;         const int s = (u.pm < ML / BM) ? (u.pm >> 5) : 4;
;         const float* bp = bias + (size_t)s * BIAS_N + u.pn * BM + wc * 32 + 8 * fq;
;         const f32x4 ba0 = *(const f32x4*)bp, ba1 = *(const f32x4*)(bp + 4), bb0 = *(const f32x4*)(bp + HALF), bb1 = *(const f32x4*)(bp + HALF + 4);
;         const int lane = fq * 16 + fr;
;         const float rsl0 = row_rstd(ss, u.pm * BM + wr * 64 + lane), rsl1 = row_rstd(ss, u.pm * BM + HALF + wr * 64 + lane);
; #pragma unroll
;         for (int ai = 0; ai < 2; ++ai)
; #pragma unroll
;             for (int m = 0; m < 4; ++m) { const int row = row0 + ai * HALF + m * 16; const float rs = __shfl(ai ? rsl1 : rsl0, m * 16 + fr); bf16_t* rowp = O + (size_t)row * DFF + col0;
;                 const f32x4 a0 = acc[ai][0][m][0] * rs + ba0, a1 = acc[ai][0][m][1] * rs + ba1, b0 = acc[ai][1][m][0] * rs + bb0, b1 = acc[ai][1][m][1] * rs + bb1;
;                 u32x4 w; w.x = cvt_pk_bf16(silu_mul(a0[0], b0[0]), silu_mul(a0[1], b0[1])); w.y = cvt_pk_bf16(silu_mul(a0[2], b0[2]), silu_mul(a0[3], b0[3]));
;                 w.z = cvt_pk_bf16(silu_mul(a1[0], b1[0]), silu_mul(a1[1], b1[1])); w.w = cvt_pk_bf16(silu_mul(a1[2], b1[2]), silu_mul(a1[3], b1[3]));
;                 *(u32x4*)rowp = w; }
.LBB0_1470:
	s_lshl_b32 s2, s2, 8
	s_add_i32 s13, s2, s42
	s_lshl_b64 s[2:3], s[16:17], 2
	s_add_u32 s15, s43, s2
	s_addc_u32 s16, s44, s3
	s_lshl_b32 s2, s0, 8
	s_ashr_i32 s3, s2, 31
	s_lshl_b64 s[2:3], s[2:3], 2
	v_lshl_or_b32 v164, s0, 7, v173
	s_add_u32 s0, s15, s2
	s_addc_u32 s3, s16, s3
	v_or_b32_e32 v162, s13, v171
	s_add_u32 s2, s0, s50
	v_ashrrev_i32_e32 v163, 31, v162
	s_addc_u32 s3, s3, 0
	v_lshl_add_u64 v[162:163], v[162:163], 2, s[64:65]
	v_mov_b32_e32 v74, v234
	v_mov_b32_e32 v75, v235
	v_mov_b32_e32 v76, v236
	v_mov_b32_e32 v77, v237
	v_mov_b32_e32 v78, v238
	v_mov_b32_e32 v79, v239
	v_mov_b32_e32 v80, v240
	v_mov_b32_e32 v81, v241
	v_mov_b32_e32 v66, v242
	v_mov_b32_e32 v67, v243
	v_mov_b32_e32 v68, v244
	v_mov_b32_e32 v69, v245
	v_mov_b32_e32 v70, v246
	v_mov_b32_e32 v71, v247
	v_mov_b32_e32 v72, v248
	v_mov_b32_e32 v73, v249
	v_or_b32_e32 v181, s13, v169
	v_mov_b32_e32 v162, v250
	v_fmamk_f32 v162, v162, 0x3a000000, v178
	v_cmp_gt_f32_e32 vcc, s51, v162
	v_mul_f32_e32 v163, 0x4f800000, v162
	s_nop 0
	v_cndmask_b32_e32 v162, v162, v163, vcc
	v_sqrt_f32_e32 v163, v162
	s_nop 0
	v_add_u32_e32 v165, -1, v163
	v_fma_f32 v166, -v165, v163, v162
	v_cmp_ge_f32_e64 s[2:3], 0, v166
	v_add_u32_e32 v166, 1, v163
	s_nop 0
	v_cndmask_b32_e64 v165, v163, v165, s[2:3]
	v_fma_f32 v163, -v166, v163, v162
	v_cmp_lt_f32_e64 s[2:3], 0, v163
	s_nop 1
	v_cndmask_b32_e64 v163, v165, v166, s[2:3]
	v_mul_f32_e32 v165, 0x37800000, v163
	v_cndmask_b32_e32 v163, v163, v165, vcc
	v_cmp_class_f32_e32 vcc, v162, v179
	s_nop 1
	v_cndmask_b32_e32 v166, v163, v162, vcc
	v_add_u32_e32 v162, s13, v172
	v_ashrrev_i32_e32 v163, 31, v162
	v_lshl_add_u64 v[162:163], v[162:163], 2, s[64:65]
	v_mov_b32_e32 v162, v251
	v_fmamk_f32 v162, v162, 0x3a000000, v178
	v_cmp_gt_f32_e32 vcc, s51, v162
	v_mul_f32_e32 v163, 0x4f800000, v162
	s_nop 0
	v_cndmask_b32_e32 v162, v162, v163, vcc
	v_sqrt_f32_e32 v163, v162
	s_nop 0
	v_add_u32_e32 v165, -1, v163
	v_fma_f32 v167, -v165, v163, v162
	v_cmp_ge_f32_e64 s[2:3], 0, v167
	v_add_u32_e32 v167, 1, v163
	s_nop 0
	v_cndmask_b32_e64 v165, v163, v165, s[2:3]
	v_fma_f32 v163, -v167, v163, v162
	v_cmp_lt_f32_e64 s[2:3], 0, v163
	s_nop 1
	v_cndmask_b32_e64 v163, v165, v167, s[2:3]
	v_mul_f32_e32 v165, 0x37800000, v163
	v_cndmask_b32_e32 v163, v163, v165, vcc
	v_cmp_class_f32_e32 vcc, v162, v179
	v_ashrrev_i32_e32 v165, 31, v164
	v_lshlrev_b64 v[164:165], 1, v[164:165]
	v_cndmask_b32_e32 v182, v163, v162, vcc
	v_div_scale_f32 v162, s[2:3], v166, v166, 1.0
	v_rcp_f32_e32 v163, v162
	s_nop 0
	v_fma_f32 v167, -v162, v163, 1.0
	v_fmac_f32_e32 v163, v167, v163
	v_div_scale_f32 v167, vcc, 1.0, v166, 1.0
	v_mul_f32_e32 v168, v167, v163
	v_fma_f32 v183, -v162, v168, v167
	v_fmac_f32_e32 v168, v183, v163
	v_fma_f32 v162, -v162, v168, v167
	v_div_fmas_f32 v162, v162, v163, v168
	v_div_fixup_f32 v183, v162, v166, 1.0
	s_and_b64 vcc, exec, s[10:11]
	s_cbranch_vccz .Lalign_1468
	s_barrier
.Lalign_1468:
	s_mov_b32 s100, 0xbfb8aa3b
	ds_bpermute_b32 v242, v180, v183
	ds_bpermute_b32 v244, v180, v183 offset:64
	ds_bpermute_b32 v246, v180, v183 offset:128
	ds_bpermute_b32 v248, v180, v183 offset:192
	v_mov_b64_e32 v[162:163], s[96:97]
	v_mad_i64_i32 v[166:167], s[2:3], v181, s49, v[162:163]
	v_lshl_add_u64 v[166:167], v[166:167], 0, v[164:165]
	s_waitcnt lgkmcnt(0)
	v_pk_fma_f32 v[142:143], v[142:143], v[242:243], v[78:79] op_sel_hi:[1,0,1]
	v_pk_fma_f32 v[144:145], v[144:145], v[242:243], v[80:81] op_sel_hi:[1,0,1]
	v_pk_fma_f32 v[134:135], v[134:135], v[242:243], v[70:71] op_sel_hi:[1,0,1]
	v_pk_fma_f32 v[136:137], v[136:137], v[242:243], v[72:73] op_sel_hi:[1,0,1]
	v_pk_fma_f32 v[138:139], v[138:139], v[242:243], v[74:75] op_sel_hi:[1,0,1]
	v_pk_fma_f32 v[140:141], v[140:141], v[242:243], v[76:77] op_sel_hi:[1,0,1]
	v_pk_fma_f32 v[130:131], v[130:131], v[242:243], v[66:67] op_sel_hi:[1,0,1]
	v_pk_fma_f32 v[132:133], v[132:133], v[242:243], v[68:69] op_sel_hi:[1,0,1]
	v_pk_mul_f32 v[234:235], v[142:143], s[100:101] op_sel_hi:[1,0]
	v_pk_mul_f32 v[236:237], v[144:145], s[100:101] op_sel_hi:[1,0]
	v_exp_f32_e32 v234, v234
	v_exp_f32_e32 v235, v235
	v_exp_f32_e32 v236, v236
	v_exp_f32_e32 v237, v237
	v_pk_add_f32 v[234:235], v[234:235], 1.0 op_sel_hi:[1,0]
	v_pk_add_f32 v[236:237], v[236:237], 1.0 op_sel_hi:[1,0]
	v_rcp_f32_e32 v234, v234
	v_rcp_f32_e32 v235, v235
	v_rcp_f32_e32 v236, v236
	v_rcp_f32_e32 v237, v237
	v_pk_mul_f32 v[134:135], v[142:143], v[134:135]
	v_pk_mul_f32 v[136:137], v[144:145], v[136:137]
	v_pk_mul_f32 v[134:135], v[134:135], v[234:235]
	v_pk_mul_f32 v[136:137], v[136:137], v[236:237]
	v_cvt_pk_bf16_f32 v238, v134, v135
	v_cvt_pk_bf16_f32 v239, v136, v137
	v_pk_mul_f32 v[234:235], v[138:139], s[100:101] op_sel_hi:[1,0]
	v_pk_mul_f32 v[236:237], v[140:141], s[100:101] op_sel_hi:[1,0]
	v_exp_f32_e32 v234, v234
	v_exp_f32_e32 v235, v235
	v_exp_f32_e32 v236, v236
	v_exp_f32_e32 v237, v237
	v_pk_add_f32 v[234:235], v[234:235], 1.0 op_sel_hi:[1,0]
	v_pk_add_f32 v[236:237], v[236:237], 1.0 op_sel_hi:[1,0]
	v_rcp_f32_e32 v234, v234
	v_rcp_f32_e32 v235, v235
	v_rcp_f32_e32 v236, v236
	v_rcp_f32_e32 v237, v237
	v_pk_mul_f32 v[130:131], v[138:139], v[130:131]
	v_pk_mul_f32 v[132:133], v[140:141], v[132:133]
	v_pk_mul_f32 v[130:131], v[130:131], v[234:235]
	v_pk_mul_f32 v[132:133], v[132:133], v[236:237]
	v_cvt_pk_bf16_f32 v240, v130, v131
	v_cvt_pk_bf16_f32 v241, v132, v133
	global_store_dwordx4 v[166:167], v[238:241], off
	v_or_b32_e32 v131, 16, v181
	v_mad_i64_i32 v[132:133], s[2:3], v131, s49, v[162:163]
	v_lshl_add_u64 v[132:133], v[132:133], 0, v[164:165]
	v_pk_fma_f32 v[126:127], v[126:127], v[244:245], v[78:79] op_sel_hi:[1,0,1]
; __device__ __forceinline__ unsigned cvt_pk_bf16(float lo, float hi) { unsigned r; asm volatile("v_cvt_pk_bf16_f32 %0, %1, %2" : "=v"(r) : "v"(lo), "v"(hi)); return r; }
; __device__ __forceinline__ float silu_mul(float a, float b) { return a * b * __builtin_amdgcn_rcpf(1.0f + __builtin_amdgcn_exp2f(-a * LOG2E)); }
;     __device__ __forceinline__ void operator()(const f32x4 (&acc)[2][2][4][2], const Unit& u, int wr, int wc, int fr, int fq) const {
;     ...
;             for (int m = 0; m < 4; ++m) { const int row = row0 + ai * HALF + m * 16; const float rs = __shfl(ai ? rsl1 : rsl0, m * 16 + fr); bf16_t* rowp = O + (size_t)row * DFF + col0;
;                 const f32x4 a0 = acc[ai][0][m][0] * rs + ba0, a1 = acc[ai][0][m][1] * rs + ba1, b0 = acc[ai][1][m][0] * rs + bb0, b1 = acc[ai][1][m][1] * rs + bb1;
;                 u32x4 w; w.x = cvt_pk_bf16(silu_mul(a0[0], b0[0]), silu_mul(a0[1], b0[1])); w.y = cvt_pk_bf16(silu_mul(a0[2], b0[2]), silu_mul(a0[3], b0[3]));
;                 w.z = cvt_pk_bf16(silu_mul(a1[0], b1[0]), silu_mul(a1[1], b1[1])); w.w = cvt_pk_bf16(silu_mul(a1[2], b1[2]), silu_mul(a1[3], b1[3]));
;                 *(u32x4*)rowp = w; }
	v_pk_fma_f32 v[128:129], v[128:129], v[244:245], v[80:81] op_sel_hi:[1,0,1]
	v_pk_fma_f32 v[118:119], v[118:119], v[244:245], v[70:71] op_sel_hi:[1,0,1]
	v_pk_fma_f32 v[120:121], v[120:121], v[244:245], v[72:73] op_sel_hi:[1,0,1]
	v_pk_fma_f32 v[122:123], v[122:123], v[244:245], v[74:75] op_sel_hi:[1,0,1]
	v_pk_fma_f32 v[124:125], v[124:125], v[244:245], v[76:77] op_sel_hi:[1,0,1]
	v_pk_fma_f32 v[114:115], v[114:115], v[244:245], v[66:67] op_sel_hi:[1,0,1]
	v_pk_fma_f32 v[116:117], v[116:117], v[244:245], v[68:69] op_sel_hi:[1,0,1]
	v_pk_mul_f32 v[234:235], v[126:127], s[100:101] op_sel_hi:[1,0]
	v_pk_mul_f32 v[236:237], v[128:129], s[100:101] op_sel_hi:[1,0]
	v_exp_f32_e32 v234, v234
	v_exp_f32_e32 v235, v235
	v_exp_f32_e32 v236, v236
	v_exp_f32_e32 v237, v237
	v_pk_add_f32 v[234:235], v[234:235], 1.0 op_sel_hi:[1,0]
	v_pk_add_f32 v[236:237], v[236:237], 1.0 op_sel_hi:[1,0]
	v_rcp_f32_e32 v234, v234
	v_rcp_f32_e32 v235, v235
	v_rcp_f32_e32 v236, v236
	v_rcp_f32_e32 v237, v237
	v_pk_mul_f32 v[118:119], v[126:127], v[118:119]
	v_pk_mul_f32 v[120:121], v[128:129], v[120:121]
	v_pk_mul_f32 v[118:119], v[118:119], v[234:235]
	v_pk_mul_f32 v[120:121], v[120:121], v[236:237]
	v_cvt_pk_bf16_f32 v238, v118, v119
	v_cvt_pk_bf16_f32 v239, v120, v121
	v_pk_mul_f32 v[234:235], v[122:123], s[100:101] op_sel_hi:[1,0]
	v_pk_mul_f32 v[236:237], v[124:125], s[100:101] op_sel_hi:[1,0]
	v_exp_f32_e32 v234, v234
	v_exp_f32_e32 v235, v235
	v_exp_f32_e32 v236, v236
	v_exp_f32_e32 v237, v237
	v_pk_add_f32 v[234:235], v[234:235], 1.0 op_sel_hi:[1,0]
	v_pk_add_f32 v[236:237], v[236:237], 1.0 op_sel_hi:[1,0]
	v_rcp_f32_e32 v234, v234
	v_rcp_f32_e32 v235, v235
	v_rcp_f32_e32 v236, v236
	v_rcp_f32_e32 v237, v237
	v_pk_mul_f32 v[114:115], v[122:123], v[114:115]
	v_pk_mul_f32 v[116:117], v[124:125], v[116:117]
	v_pk_mul_f32 v[114:115], v[114:115], v[234:235]
	v_pk_mul_f32 v[116:117], v[116:117], v[236:237]
	v_cvt_pk_bf16_f32 v240, v114, v115
	v_cvt_pk_bf16_f32 v241, v116, v117
	global_store_dwordx4 v[132:133], v[238:241], off
	v_or_b32_e32 v115, 32, v181
	v_mad_i64_i32 v[116:117], s[2:3], v115, s49, v[162:163]
	v_lshl_add_u64 v[116:117], v[116:117], 0, v[164:165]
	v_pk_fma_f32 v[110:111], v[110:111], v[246:247], v[78:79] op_sel_hi:[1,0,1]
	v_pk_fma_f32 v[112:113], v[112:113], v[246:247], v[80:81] op_sel_hi:[1,0,1]
	v_pk_fma_f32 v[102:103], v[102:103], v[246:247], v[70:71] op_sel_hi:[1,0,1]
	v_pk_fma_f32 v[104:105], v[104:105], v[246:247], v[72:73] op_sel_hi:[1,0,1]
	v_pk_fma_f32 v[106:107], v[106:107], v[246:247], v[74:75] op_sel_hi:[1,0,1]
	v_pk_fma_f32 v[108:109], v[108:109], v[246:247], v[76:77] op_sel_hi:[1,0,1]
	v_pk_fma_f32 v[98:99], v[98:99], v[246:247], v[66:67] op_sel_hi:[1,0,1]
	v_pk_fma_f32 v[100:101], v[100:101], v[246:247], v[68:69] op_sel_hi:[1,0,1]
	v_pk_mul_f32 v[234:235], v[110:111], s[100:101] op_sel_hi:[1,0]
	v_pk_mul_f32 v[236:237], v[112:113], s[100:101] op_sel_hi:[1,0]
	v_exp_f32_e32 v234, v234
	v_exp_f32_e32 v235, v235
	v_exp_f32_e32 v236, v236
	v_exp_f32_e32 v237, v237
	v_pk_add_f32 v[234:235], v[234:235], 1.0 op_sel_hi:[1,0]
	v_pk_add_f32 v[236:237], v[236:237], 1.0 op_sel_hi:[1,0]
	v_rcp_f32_e32 v234, v234
	v_rcp_f32_e32 v235, v235
	v_rcp_f32_e32 v236, v236
	v_rcp_f32_e32 v237, v237
	v_pk_mul_f32 v[102:103], v[110:111], v[102:103]
	v_pk_mul_f32 v[104:105], v[112:113], v[104:105]
	v_pk_mul_f32 v[102:103], v[102:103], v[234:235]
	v_pk_mul_f32 v[104:105], v[104:105], v[236:237]
	v_cvt_pk_bf16_f32 v238, v102, v103
	v_cvt_pk_bf16_f32 v239, v104, v105
	v_pk_mul_f32 v[234:235], v[106:107], s[100:101] op_sel_hi:[1,0]
	v_pk_mul_f32 v[236:237], v[108:109], s[100:101] op_sel_hi:[1,0]
	v_exp_f32_e32 v234, v234
	v_exp_f32_e32 v235, v235
	v_exp_f32_e32 v236, v236
	v_exp_f32_e32 v237, v237
	v_pk_add_f32 v[234:235], v[234:235], 1.0 op_sel_hi:[1,0]
	v_pk_add_f32 v[236:237], v[236:237], 1.0 op_sel_hi:[1,0]
	v_rcp_f32_e32 v234, v234
	v_rcp_f32_e32 v235, v235
	v_rcp_f32_e32 v236, v236
	v_rcp_f32_e32 v237, v237
	v_pk_mul_f32 v[98:99], v[106:107], v[98:99]
	v_pk_mul_f32 v[100:101], v[108:109], v[100:101]
	v_pk_mul_f32 v[98:99], v[98:99], v[234:235]
	v_pk_mul_f32 v[100:101], v[100:101], v[236:237]
	v_cvt_pk_bf16_f32 v240, v98, v99
	v_cvt_pk_bf16_f32 v241, v100, v101
	global_store_dwordx4 v[116:117], v[238:241], off
	v_or_b32_e32 v99, 48, v181
	v_mad_i64_i32 v[100:101], s[2:3], v99, s49, v[162:163]
	v_lshl_add_u64 v[100:101], v[100:101], 0, v[164:165]
	v_pk_fma_f32 v[94:95], v[94:95], v[248:249], v[78:79] op_sel_hi:[1,0,1]
	v_pk_fma_f32 v[96:97], v[96:97], v[248:249], v[80:81] op_sel_hi:[1,0,1]
	v_pk_fma_f32 v[86:87], v[86:87], v[248:249], v[70:71] op_sel_hi:[1,0,1]
	v_pk_fma_f32 v[88:89], v[88:89], v[248:249], v[72:73] op_sel_hi:[1,0,1]
	v_pk_fma_f32 v[90:91], v[90:91], v[248:249], v[74:75] op_sel_hi:[1,0,1]
	v_pk_fma_f32 v[92:93], v[92:93], v[248:249], v[76:77] op_sel_hi:[1,0,1]
	v_pk_fma_f32 v[82:83], v[82:83], v[248:249], v[66:67] op_sel_hi:[1,0,1]
	v_pk_fma_f32 v[84:85], v[84:85], v[248:249], v[68:69] op_sel_hi:[1,0,1]
	v_pk_mul_f32 v[234:235], v[94:95], s[100:101] op_sel_hi:[1,0]
	v_pk_mul_f32 v[236:237], v[96:97], s[100:101] op_sel_hi:[1,0]
	v_exp_f32_e32 v234, v234
	v_exp_f32_e32 v235, v235
	v_exp_f32_e32 v236, v236
	v_exp_f32_e32 v237, v237
	v_pk_add_f32 v[234:235], v[234:235], 1.0 op_sel_hi:[1,0]
	v_pk_add_f32 v[236:237], v[236:237], 1.0 op_sel_hi:[1,0]
	v_rcp_f32_e32 v234, v234
	v_rcp_f32_e32 v235, v235
	v_rcp_f32_e32 v236, v236
	v_rcp_f32_e32 v237, v237
	v_pk_mul_f32 v[86:87], v[94:95], v[86:87]
	v_pk_mul_f32 v[88:89], v[96:97], v[88:89]
	v_pk_mul_f32 v[86:87], v[86:87], v[234:235]
	v_pk_mul_f32 v[88:89], v[88:89], v[236:237]
	v_cvt_pk_bf16_f32 v238, v86, v87
; __device__ __forceinline__ unsigned cvt_pk_bf16(float lo, float hi) { unsigned r; asm volatile("v_cvt_pk_bf16_f32 %0, %1, %2" : "=v"(r) : "v"(lo), "v"(hi)); return r; }
; __device__ __forceinline__ float row_rstd(const float* ss, int row) { return 1.0f / sqrtf(ss[row] * (1.0f / DM) + 1e-6f); }
; __device__ __forceinline__ float silu_mul(float a, float b) { return a * b * __builtin_amdgcn_rcpf(1.0f + __builtin_amdgcn_exp2f(-a * LOG2E)); }
;     __device__ __forceinline__ void operator()(const f32x4 (&acc)[2][2][4][2], const Unit& u, int wr, int wc, int fr, int fq) const {
;     ...
;         const float rsl0 = row_rstd(ss, u.pm * BM + wr * 64 + lane), rsl1 = row_rstd(ss, u.pm * BM + HALF + wr * 64 + lane);
; #pragma unroll
;         for (int ai = 0; ai < 2; ++ai)
; #pragma unroll
;             for (int m = 0; m < 4; ++m) { const int row = row0 + ai * HALF + m * 16; const float rs = __shfl(ai ? rsl1 : rsl0, m * 16 + fr); bf16_t* rowp = O + (size_t)row * DFF + col0;
;                 const f32x4 a0 = acc[ai][0][m][0] * rs + ba0, a1 = acc[ai][0][m][1] * rs + ba1, b0 = acc[ai][1][m][0] * rs + bb0, b1 = acc[ai][1][m][1] * rs + bb1;
;                 u32x4 w; w.x = cvt_pk_bf16(silu_mul(a0[0], b0[0]), silu_mul(a0[1], b0[1])); w.y = cvt_pk_bf16(silu_mul(a0[2], b0[2]), silu_mul(a0[3], b0[3]));
;                 w.z = cvt_pk_bf16(silu_mul(a1[0], b1[0]), silu_mul(a1[1], b1[1])); w.w = cvt_pk_bf16(silu_mul(a1[2], b1[2]), silu_mul(a1[3], b1[3]));
;                 *(u32x4*)rowp = w; }
	v_cvt_pk_bf16_f32 v239, v88, v89
	v_pk_mul_f32 v[234:235], v[90:91], s[100:101] op_sel_hi:[1,0]
	v_pk_mul_f32 v[236:237], v[92:93], s[100:101] op_sel_hi:[1,0]
	v_exp_f32_e32 v234, v234
	v_exp_f32_e32 v235, v235
	v_exp_f32_e32 v236, v236
	v_exp_f32_e32 v237, v237
	v_pk_add_f32 v[234:235], v[234:235], 1.0 op_sel_hi:[1,0]
	v_pk_add_f32 v[236:237], v[236:237], 1.0 op_sel_hi:[1,0]
	v_rcp_f32_e32 v234, v234
	v_rcp_f32_e32 v235, v235
	v_rcp_f32_e32 v236, v236
	v_rcp_f32_e32 v237, v237
	v_pk_mul_f32 v[82:83], v[90:91], v[82:83]
	v_pk_mul_f32 v[84:85], v[92:93], v[84:85]
	v_pk_mul_f32 v[82:83], v[82:83], v[234:235]
	v_pk_mul_f32 v[84:85], v[84:85], v[236:237]
	v_cvt_pk_bf16_f32 v240, v82, v83
	v_cvt_pk_bf16_f32 v241, v84, v85
	global_store_dwordx4 v[100:101], v[238:241], off
	s_nop 1
	v_div_scale_f32 v82, s[2:3], v182, v182, 1.0
	v_rcp_f32_e32 v84, v82
	v_add_u32_e32 v83, 0x80, v181
	v_fma_f32 v85, -v82, v84, 1.0
	v_fmac_f32_e32 v84, v85, v84
	v_div_scale_f32 v85, vcc, 1.0, v182, 1.0
	v_mul_f32_e32 v86, v85, v84
	v_fma_f32 v87, -v82, v86, v85
	v_fmac_f32_e32 v86, v87, v84
	v_fma_f32 v82, -v82, v86, v85
	v_div_fmas_f32 v82, v82, v84, v86
	v_div_fixup_f32 v82, v82, v182, 1.0
	ds_bpermute_b32 v242, v180, v82
	ds_bpermute_b32 v244, v180, v82 offset:64
	ds_bpermute_b32 v246, v180, v82 offset:128
	ds_bpermute_b32 v248, v180, v82 offset:192
	v_mad_i64_i32 v[86:87], s[2:3], v83, s49, v[162:163]
	v_lshl_add_u64 v[86:87], v[86:87], 0, v[164:165]
	s_andn2_b64 vcc, exec, s[38:39]
	s_waitcnt lgkmcnt(0)
	v_pk_fma_f32 v[62:63], v[62:63], v[242:243], v[78:79] op_sel_hi:[1,0,1]
	v_pk_fma_f32 v[64:65], v[64:65], v[242:243], v[80:81] op_sel_hi:[1,0,1]
	v_pk_fma_f32 v[54:55], v[54:55], v[242:243], v[70:71] op_sel_hi:[1,0,1]
	v_pk_fma_f32 v[56:57], v[56:57], v[242:243], v[72:73] op_sel_hi:[1,0,1]
	v_pk_fma_f32 v[58:59], v[58:59], v[242:243], v[74:75] op_sel_hi:[1,0,1]
	v_pk_fma_f32 v[60:61], v[60:61], v[242:243], v[76:77] op_sel_hi:[1,0,1]
	v_pk_fma_f32 v[50:51], v[50:51], v[242:243], v[66:67] op_sel_hi:[1,0,1]
	v_pk_fma_f32 v[52:53], v[52:53], v[242:243], v[68:69] op_sel_hi:[1,0,1]
	v_pk_mul_f32 v[234:235], v[62:63], s[100:101] op_sel_hi:[1,0]
	v_pk_mul_f32 v[236:237], v[64:65], s[100:101] op_sel_hi:[1,0]
	v_exp_f32_e32 v234, v234
	v_exp_f32_e32 v235, v235
	v_exp_f32_e32 v236, v236
	v_exp_f32_e32 v237, v237
	v_pk_add_f32 v[234:235], v[234:235], 1.0 op_sel_hi:[1,0]
	v_pk_add_f32 v[236:237], v[236:237], 1.0 op_sel_hi:[1,0]
	v_rcp_f32_e32 v234, v234
	v_rcp_f32_e32 v235, v235
	v_rcp_f32_e32 v236, v236
	v_rcp_f32_e32 v237, v237
	v_pk_mul_f32 v[54:55], v[62:63], v[54:55]
	v_pk_mul_f32 v[56:57], v[64:65], v[56:57]
	v_pk_mul_f32 v[54:55], v[54:55], v[234:235]
	v_pk_mul_f32 v[56:57], v[56:57], v[236:237]
	v_cvt_pk_bf16_f32 v238, v54, v55
	v_cvt_pk_bf16_f32 v239, v56, v57
	v_pk_mul_f32 v[234:235], v[58:59], s[100:101] op_sel_hi:[1,0]
	v_pk_mul_f32 v[236:237], v[60:61], s[100:101] op_sel_hi:[1,0]
	v_exp_f32_e32 v234, v234
	v_exp_f32_e32 v235, v235
	v_exp_f32_e32 v236, v236
	v_exp_f32_e32 v237, v237
	v_pk_add_f32 v[234:235], v[234:235], 1.0 op_sel_hi:[1,0]
	v_pk_add_f32 v[236:237], v[236:237], 1.0 op_sel_hi:[1,0]
	v_rcp_f32_e32 v234, v234
	v_rcp_f32_e32 v235, v235
	v_rcp_f32_e32 v236, v236
	v_rcp_f32_e32 v237, v237
	v_pk_mul_f32 v[50:51], v[58:59], v[50:51]
	v_pk_mul_f32 v[52:53], v[60:61], v[52:53]
	v_pk_mul_f32 v[50:51], v[50:51], v[234:235]
	v_pk_mul_f32 v[52:53], v[52:53], v[236:237]
	v_cvt_pk_bf16_f32 v240, v50, v51
	v_cvt_pk_bf16_f32 v241, v52, v53
	global_store_dwordx4 v[86:87], v[238:241], off
	v_add_u32_e32 v51, 0x90, v181
	v_mad_i64_i32 v[52:53], s[2:3], v51, s49, v[162:163]
	v_lshl_add_u64 v[52:53], v[52:53], 0, v[164:165]
	v_pk_fma_f32 v[46:47], v[46:47], v[244:245], v[78:79] op_sel_hi:[1,0,1]
	v_pk_fma_f32 v[48:49], v[48:49], v[244:245], v[80:81] op_sel_hi:[1,0,1]
	v_pk_fma_f32 v[38:39], v[38:39], v[244:245], v[70:71] op_sel_hi:[1,0,1]
	v_pk_fma_f32 v[40:41], v[40:41], v[244:245], v[72:73] op_sel_hi:[1,0,1]
	v_pk_fma_f32 v[42:43], v[42:43], v[244:245], v[74:75] op_sel_hi:[1,0,1]
	v_pk_fma_f32 v[44:45], v[44:45], v[244:245], v[76:77] op_sel_hi:[1,0,1]
	v_pk_fma_f32 v[34:35], v[34:35], v[244:245], v[66:67] op_sel_hi:[1,0,1]
	v_pk_fma_f32 v[36:37], v[36:37], v[244:245], v[68:69] op_sel_hi:[1,0,1]
	v_pk_mul_f32 v[234:235], v[46:47], s[100:101] op_sel_hi:[1,0]
	v_pk_mul_f32 v[236:237], v[48:49], s[100:101] op_sel_hi:[1,0]
	v_exp_f32_e32 v234, v234
	v_exp_f32_e32 v235, v235
	v_exp_f32_e32 v236, v236
	v_exp_f32_e32 v237, v237
	v_pk_add_f32 v[234:235], v[234:235], 1.0 op_sel_hi:[1,0]
	v_pk_add_f32 v[236:237], v[236:237], 1.0 op_sel_hi:[1,0]
	v_rcp_f32_e32 v234, v234
	v_rcp_f32_e32 v235, v235
	v_rcp_f32_e32 v236, v236
	v_rcp_f32_e32 v237, v237
	v_pk_mul_f32 v[38:39], v[46:47], v[38:39]
	v_pk_mul_f32 v[40:41], v[48:49], v[40:41]
	v_pk_mul_f32 v[38:39], v[38:39], v[234:235]
	v_pk_mul_f32 v[40:41], v[40:41], v[236:237]
	v_cvt_pk_bf16_f32 v238, v38, v39
	v_cvt_pk_bf16_f32 v239, v40, v41
	v_pk_mul_f32 v[234:235], v[42:43], s[100:101] op_sel_hi:[1,0]
	v_pk_mul_f32 v[236:237], v[44:45], s[100:101] op_sel_hi:[1,0]
; __device__ __forceinline__ unsigned cvt_pk_bf16(float lo, float hi) { unsigned r; asm volatile("v_cvt_pk_bf16_f32 %0, %1, %2" : "=v"(r) : "v"(lo), "v"(hi)); return r; }
; __device__ __forceinline__ float silu_mul(float a, float b) { return a * b * __builtin_amdgcn_rcpf(1.0f + __builtin_amdgcn_exp2f(-a * LOG2E)); }
; #define PG8_BAR __builtin_amdgcn_s_barrier()
;     __device__ __forceinline__ void operator()(const f32x4 (&acc)[2][2][4][2], const Unit& u, int wr, int wc, int fr, int fq) const {
;     ...
;             for (int m = 0; m < 4; ++m) { const int row = row0 + ai * HALF + m * 16; const float rs = __shfl(ai ? rsl1 : rsl0, m * 16 + fr); bf16_t* rowp = O + (size_t)row * DFF + col0;
;                 const f32x4 a0 = acc[ai][0][m][0] * rs + ba0, a1 = acc[ai][0][m][1] * rs + ba1, b0 = acc[ai][1][m][0] * rs + bb0, b1 = acc[ai][1][m][1] * rs + bb1;
;                 u32x4 w; w.x = cvt_pk_bf16(silu_mul(a0[0], b0[0]), silu_mul(a0[1], b0[1])); w.y = cvt_pk_bf16(silu_mul(a0[2], b0[2]), silu_mul(a0[3], b0[3]));
;                 w.z = cvt_pk_bf16(silu_mul(a1[0], b1[0]), silu_mul(a1[1], b1[1])); w.w = cvt_pk_bf16(silu_mul(a1[2], b1[2]), silu_mul(a1[3], b1[3]));
;                 *(u32x4*)rowp = w; }
; template <class Epi, class Sched, bool ALIGN_EPI = false, bool SP2 = false>
; __device__ __forceinline__ void gemm_phase(LAS unsigned char* lds, const Gemm g, const Sched& S, const Epi& E) {
;     ...
;         if constexpr (!Epi::AFTER_DRAIN) { E(acc, cur, wr, wc, fr, fq); S.done(cur); }
;         if (!has_next) break;
; #pragma unroll
;         for (int a = 0; a < 2; ++a)
; #pragma unroll
;             for (int b = 0; b < 2; ++b)
; #pragma unroll
;                 for (int m = 0; m < 4; ++m)
; #pragma unroll
;                     for (int n = 0; n < 2; ++n) acc[a][b][m][n] = (f32x4){0.f, 0.f, 0.f, 0.f};
;         cur = nxt; cA = nA; cB = nB; ++ui;
;         if constexpr (ALIGN_EPI) { if (wr == 1) PG8_BAR; }
	v_exp_f32_e32 v234, v234
	v_exp_f32_e32 v235, v235
	v_exp_f32_e32 v236, v236
	v_exp_f32_e32 v237, v237
	v_pk_add_f32 v[234:235], v[234:235], 1.0 op_sel_hi:[1,0]
	v_pk_add_f32 v[236:237], v[236:237], 1.0 op_sel_hi:[1,0]
	v_rcp_f32_e32 v234, v234
	v_rcp_f32_e32 v235, v235
	v_rcp_f32_e32 v236, v236
	v_rcp_f32_e32 v237, v237
	v_pk_mul_f32 v[34:35], v[42:43], v[34:35]
	v_pk_mul_f32 v[36:37], v[44:45], v[36:37]
	v_pk_mul_f32 v[34:35], v[34:35], v[234:235]
	v_pk_mul_f32 v[36:37], v[36:37], v[236:237]
	v_cvt_pk_bf16_f32 v240, v34, v35
	v_cvt_pk_bf16_f32 v241, v36, v37
	global_store_dwordx4 v[52:53], v[238:241], off
	v_add_u32_e32 v35, 0xa0, v181
	v_mad_i64_i32 v[36:37], s[2:3], v35, s49, v[162:163]
	v_lshl_add_u64 v[36:37], v[36:37], 0, v[164:165]
	v_pk_fma_f32 v[30:31], v[30:31], v[246:247], v[78:79] op_sel_hi:[1,0,1]
	v_pk_fma_f32 v[32:33], v[32:33], v[246:247], v[80:81] op_sel_hi:[1,0,1]
	v_pk_fma_f32 v[22:23], v[22:23], v[246:247], v[70:71] op_sel_hi:[1,0,1]
	v_pk_fma_f32 v[24:25], v[24:25], v[246:247], v[72:73] op_sel_hi:[1,0,1]
	v_pk_fma_f32 v[26:27], v[26:27], v[246:247], v[74:75] op_sel_hi:[1,0,1]
	v_pk_fma_f32 v[28:29], v[28:29], v[246:247], v[76:77] op_sel_hi:[1,0,1]
	v_pk_fma_f32 v[18:19], v[18:19], v[246:247], v[66:67] op_sel_hi:[1,0,1]
	v_pk_fma_f32 v[20:21], v[20:21], v[246:247], v[68:69] op_sel_hi:[1,0,1]
	v_pk_mul_f32 v[234:235], v[30:31], s[100:101] op_sel_hi:[1,0]
	v_pk_mul_f32 v[236:237], v[32:33], s[100:101] op_sel_hi:[1,0]
	v_exp_f32_e32 v234, v234
	v_exp_f32_e32 v235, v235
	v_exp_f32_e32 v236, v236
	v_exp_f32_e32 v237, v237
	v_pk_add_f32 v[234:235], v[234:235], 1.0 op_sel_hi:[1,0]
	v_pk_add_f32 v[236:237], v[236:237], 1.0 op_sel_hi:[1,0]
	v_rcp_f32_e32 v234, v234
	v_rcp_f32_e32 v235, v235
	v_rcp_f32_e32 v236, v236
	v_rcp_f32_e32 v237, v237
	v_pk_mul_f32 v[22:23], v[30:31], v[22:23]
	v_pk_mul_f32 v[24:25], v[32:33], v[24:25]
	v_pk_mul_f32 v[22:23], v[22:23], v[234:235]
	v_pk_mul_f32 v[24:25], v[24:25], v[236:237]
	v_cvt_pk_bf16_f32 v238, v22, v23
	v_cvt_pk_bf16_f32 v239, v24, v25
	v_pk_mul_f32 v[234:235], v[26:27], s[100:101] op_sel_hi:[1,0]
	v_pk_mul_f32 v[236:237], v[28:29], s[100:101] op_sel_hi:[1,0]
	v_exp_f32_e32 v234, v234
	v_exp_f32_e32 v235, v235
	v_exp_f32_e32 v236, v236
	v_exp_f32_e32 v237, v237
	v_pk_add_f32 v[234:235], v[234:235], 1.0 op_sel_hi:[1,0]
	v_pk_add_f32 v[236:237], v[236:237], 1.0 op_sel_hi:[1,0]
	v_rcp_f32_e32 v234, v234
	v_rcp_f32_e32 v235, v235
	v_rcp_f32_e32 v236, v236
	v_rcp_f32_e32 v237, v237
	v_pk_mul_f32 v[18:19], v[26:27], v[18:19]
	v_pk_mul_f32 v[20:21], v[28:29], v[20:21]
	v_pk_mul_f32 v[18:19], v[18:19], v[234:235]
	v_pk_mul_f32 v[20:21], v[20:21], v[236:237]
	v_cvt_pk_bf16_f32 v240, v18, v19
	v_cvt_pk_bf16_f32 v241, v20, v21
	global_store_dwordx4 v[36:37], v[238:241], off
	v_add_u32_e32 v19, 0xb0, v181
	v_mad_i64_i32 v[20:21], s[2:3], v19, s49, v[162:163]
	v_lshl_add_u64 v[20:21], v[20:21], 0, v[164:165]
	s_mov_b64 s[2:3], -1
	v_pk_fma_f32 v[14:15], v[14:15], v[248:249], v[78:79] op_sel_hi:[1,0,1]
	v_pk_fma_f32 v[16:17], v[16:17], v[248:249], v[80:81] op_sel_hi:[1,0,1]
	v_pk_fma_f32 v[6:7], v[6:7], v[248:249], v[70:71] op_sel_hi:[1,0,1]
	v_pk_fma_f32 v[8:9], v[8:9], v[248:249], v[72:73] op_sel_hi:[1,0,1]
	v_pk_fma_f32 v[10:11], v[10:11], v[248:249], v[74:75] op_sel_hi:[1,0,1]
	v_pk_fma_f32 v[12:13], v[12:13], v[248:249], v[76:77] op_sel_hi:[1,0,1]
	v_pk_fma_f32 v[2:3], v[2:3], v[248:249], v[66:67] op_sel_hi:[1,0,1]
	v_pk_fma_f32 v[4:5], v[4:5], v[248:249], v[68:69] op_sel_hi:[1,0,1]
	v_pk_mul_f32 v[234:235], v[14:15], s[100:101] op_sel_hi:[1,0]
	v_pk_mul_f32 v[236:237], v[16:17], s[100:101] op_sel_hi:[1,0]
	v_exp_f32_e32 v234, v234
	v_exp_f32_e32 v235, v235
	v_exp_f32_e32 v236, v236
	v_exp_f32_e32 v237, v237
	v_pk_add_f32 v[234:235], v[234:235], 1.0 op_sel_hi:[1,0]
	v_pk_add_f32 v[236:237], v[236:237], 1.0 op_sel_hi:[1,0]
	v_rcp_f32_e32 v234, v234
	v_rcp_f32_e32 v235, v235
	v_rcp_f32_e32 v236, v236
	v_rcp_f32_e32 v237, v237
	v_pk_mul_f32 v[6:7], v[14:15], v[6:7]
	v_pk_mul_f32 v[8:9], v[16:17], v[8:9]
	v_pk_mul_f32 v[6:7], v[6:7], v[234:235]
	v_pk_mul_f32 v[8:9], v[8:9], v[236:237]
	v_cvt_pk_bf16_f32 v238, v6, v7
	v_cvt_pk_bf16_f32 v239, v8, v9
	v_pk_mul_f32 v[234:235], v[10:11], s[100:101] op_sel_hi:[1,0]
	v_pk_mul_f32 v[236:237], v[12:13], s[100:101] op_sel_hi:[1,0]
	v_exp_f32_e32 v234, v234
	v_exp_f32_e32 v235, v235
	v_exp_f32_e32 v236, v236
	v_exp_f32_e32 v237, v237
	v_pk_add_f32 v[234:235], v[234:235], 1.0 op_sel_hi:[1,0]
	v_pk_add_f32 v[236:237], v[236:237], 1.0 op_sel_hi:[1,0]
	v_rcp_f32_e32 v234, v234
	v_rcp_f32_e32 v235, v235
	v_rcp_f32_e32 v236, v236
	v_rcp_f32_e32 v237, v237
	v_pk_mul_f32 v[2:3], v[10:11], v[2:3]
	v_pk_mul_f32 v[4:5], v[12:13], v[4:5]
	v_pk_mul_f32 v[2:3], v[2:3], v[234:235]
	v_pk_mul_f32 v[4:5], v[4:5], v[236:237]
	v_cvt_pk_bf16_f32 v240, v2, v3
	v_cvt_pk_bf16_f32 v241, v4, v5
	global_store_dwordx4 v[20:21], v[238:241], off
	s_waitcnt vmcnt(8)
	s_cbranch_vccnz .LBB0_1461
	s_andn2_b64 vcc, exec, s[4:5]
	s_cbranch_vccnz .LBB0_1460
	s_barrier
	s_branch .LBB0_1460

; __device__ __forceinline__ unsigned cvt_pk_bf16(float lo, float hi) { unsigned r; asm volatile("v_cvt_pk_bf16_f32 %0, %1, %2" : "=v"(r) : "v"(lo), "v"(hi)); return r; }
; __device__ __forceinline__ float silu_mul(float a, float b) { return a * b * __builtin_amdgcn_rcpf(1.0f + __builtin_amdgcn_exp2f(-a * LOG2E)); }
; __device__ __forceinline__ float row_rstd(const float* ss, int row) { return 1.0f / sqrtf(ss[row] * (1.0f / DM) + 1e-6f); }
;     __device__ __forceinline__ void operator()(const f32x4 (&acc)[2][2][4][2], const Unit& u, int wr, int wc, int fr, int fq) const {
;         const int row0 = u.pm * BM + wr * 64 + fr, col0 = u.pn * HALF + wc * 32 + 8 * fq;
;         const int s = (u.pm < ML / BM) ? (u.pm >> 5) : 4;
;         const float* bp = bias + (size_t)s * BIAS_N + u.pn * BM + wc * 32 + 8 * fq;
;         const f32x4 ba0 = *(const f32x4*)bp, ba1 = *(const f32x4*)(bp + 4), bb0 = *(const f32x4*)(bp + HALF), bb1 = *(const f32x4*)(bp + HALF + 4);
;         const int lane = fq * 16 + fr;
;         const float rsl0 = row_rstd(ss, u.pm * BM + wr * 64 + lane), rsl1 = row_rstd(ss, u.pm * BM + HALF + wr * 64 + lane);
; #pragma unroll
;         for (int ai = 0; ai < 2; ++ai)
; #pragma unroll
;             for (int m = 0; m < 4; ++m) { const int row = row0 + ai * HALF + m * 16; const float rs = __shfl(ai ? rsl1 : rsl0, m * 16 + fr); bf16_t* rowp = O + (size_t)row * DFF + col0;
;                 const f32x4 a0 = acc[ai][0][m][0] * rs + ba0, a1 = acc[ai][0][m][1] * rs + ba1, b0 = acc[ai][1][m][0] * rs + bb0, b1 = acc[ai][1][m][1] * rs + bb1;
;                 u32x4 w; w.x = cvt_pk_bf16(silu_mul(a0[0], b0[0]), silu_mul(a0[1], b0[1])); w.y = cvt_pk_bf16(silu_mul(a0[2], b0[2]), silu_mul(a0[3], b0[3]));
;                 w.z = cvt_pk_bf16(silu_mul(a1[0], b1[0]), silu_mul(a1[1], b1[1])); w.w = cvt_pk_bf16(silu_mul(a1[2], b1[2]), silu_mul(a1[3], b1[3]));
;                 *(u32x4*)rowp = w; }
.LBB0_1827:
	s_lshl_b32 s2, s2, 8
	s_add_i32 s13, s2, s35
	s_lshl_b64 s[2:3], s[16:17], 2
	s_add_u32 s15, s36, s2
	s_addc_u32 s16, s37, s3
	s_lshl_b32 s2, s0, 8
	s_ashr_i32 s3, s2, 31
	s_lshl_b64 s[2:3], s[2:3], 2
	v_lshl_or_b32 v164, s0, 7, v172
	s_add_u32 s0, s15, s2
	s_addc_u32 s3, s16, s3
	v_or_b32_e32 v162, s13, v170
	s_add_u32 s2, s0, s47
	v_ashrrev_i32_e32 v163, 31, v162
	s_addc_u32 s3, s3, 0
	v_lshl_add_u64 v[162:163], v[162:163], 2, s[6:7]
	v_mov_b32_e32 v74, v234
	v_mov_b32_e32 v75, v235
	v_mov_b32_e32 v76, v236
	v_mov_b32_e32 v77, v237
	v_mov_b32_e32 v78, v238
	v_mov_b32_e32 v79, v239
	v_mov_b32_e32 v80, v240
	v_mov_b32_e32 v81, v241
	v_mov_b32_e32 v66, v242
	v_mov_b32_e32 v67, v243
	v_mov_b32_e32 v68, v244
	v_mov_b32_e32 v69, v245
	v_mov_b32_e32 v70, v246
	v_mov_b32_e32 v71, v247
	v_mov_b32_e32 v72, v248
	v_mov_b32_e32 v73, v249
	v_or_b32_e32 v180, s13, v1
	v_mov_b32_e32 v162, v250
	v_fmamk_f32 v162, v162, 0x3a000000, v177
	v_cmp_gt_f32_e32 vcc, s48, v162
	v_mul_f32_e32 v163, 0x4f800000, v162
	s_nop 0
	v_cndmask_b32_e32 v162, v162, v163, vcc
	v_sqrt_f32_e32 v163, v162
	s_nop 0
	v_add_u32_e32 v165, -1, v163
	v_fma_f32 v166, -v165, v163, v162
	v_cmp_ge_f32_e64 s[2:3], 0, v166
	v_add_u32_e32 v166, 1, v163
	s_nop 0
	v_cndmask_b32_e64 v165, v163, v165, s[2:3]
	v_fma_f32 v163, -v166, v163, v162
	v_cmp_lt_f32_e64 s[2:3], 0, v163
	s_nop 1
	v_cndmask_b32_e64 v163, v165, v166, s[2:3]
	v_mul_f32_e32 v165, 0x37800000, v163
	v_cndmask_b32_e32 v163, v163, v165, vcc
	v_cmp_class_f32_e32 vcc, v162, v178
	s_nop 1
	v_cndmask_b32_e32 v166, v163, v162, vcc
	v_add_u32_e32 v162, s13, v171
	v_ashrrev_i32_e32 v163, 31, v162
	v_lshl_add_u64 v[162:163], v[162:163], 2, s[6:7]
	v_mov_b32_e32 v162, v251
	v_fmamk_f32 v162, v162, 0x3a000000, v177
	v_cmp_gt_f32_e32 vcc, s48, v162
	v_mul_f32_e32 v163, 0x4f800000, v162
	s_nop 0
	v_cndmask_b32_e32 v162, v162, v163, vcc
	v_sqrt_f32_e32 v163, v162
	s_nop 0
	v_add_u32_e32 v165, -1, v163
	v_fma_f32 v167, -v165, v163, v162
	v_cmp_ge_f32_e64 s[2:3], 0, v167
	v_add_u32_e32 v167, 1, v163
	s_nop 0
	v_cndmask_b32_e64 v165, v163, v165, s[2:3]
	v_fma_f32 v163, -v167, v163, v162
	v_cmp_lt_f32_e64 s[2:3], 0, v163
	s_nop 1
	v_cndmask_b32_e64 v163, v165, v167, s[2:3]
	v_mul_f32_e32 v165, 0x37800000, v163
	v_cndmask_b32_e32 v163, v163, v165, vcc
	v_cmp_class_f32_e32 vcc, v162, v178
	v_ashrrev_i32_e32 v165, 31, v164
	v_lshlrev_b64 v[164:165], 1, v[164:165]
	v_cndmask_b32_e32 v181, v163, v162, vcc
	v_div_scale_f32 v162, s[2:3], v166, v166, 1.0
	v_rcp_f32_e32 v163, v162
	s_nop 0
	v_fma_f32 v167, -v162, v163, 1.0
	v_fmac_f32_e32 v163, v167, v163
	v_div_scale_f32 v167, vcc, 1.0, v166, 1.0
	v_mul_f32_e32 v168, v167, v163
	v_fma_f32 v182, -v162, v168, v167
	v_fmac_f32_e32 v168, v182, v163
	v_fma_f32 v162, -v162, v168, v167
	v_div_fmas_f32 v162, v162, v163, v168
	v_div_fixup_f32 v182, v162, v166, 1.0
	s_andn2_b64 vcc, exec, s[10:11]
	s_cbranch_vccnz .Lalign_1825
	s_barrier
.Lalign_1825:
	s_mov_b32 s100, 0xbfb8aa3b
	ds_bpermute_b32 v242, v179, v182
	ds_bpermute_b32 v244, v179, v182 offset:64
	ds_bpermute_b32 v246, v179, v182 offset:128
	ds_bpermute_b32 v248, v179, v182 offset:192
	v_mov_b64_e32 v[162:163], s[96:97]
	v_mad_i64_i32 v[166:167], s[2:3], v180, s46, v[162:163]
	v_lshl_add_u64 v[166:167], v[166:167], 0, v[164:165]
	s_waitcnt lgkmcnt(0)
	v_pk_fma_f32 v[142:143], v[142:143], v[242:243], v[78:79] op_sel_hi:[1,0,1]
	v_pk_fma_f32 v[144:145], v[144:145], v[242:243], v[80:81] op_sel_hi:[1,0,1]
	v_pk_fma_f32 v[134:135], v[134:135], v[242:243], v[70:71] op_sel_hi:[1,0,1]
	v_pk_fma_f32 v[136:137], v[136:137], v[242:243], v[72:73] op_sel_hi:[1,0,1]
	v_pk_fma_f32 v[138:139], v[138:139], v[242:243], v[74:75] op_sel_hi:[1,0,1]
	v_pk_fma_f32 v[140:141], v[140:141], v[242:243], v[76:77] op_sel_hi:[1,0,1]
	v_pk_fma_f32 v[130:131], v[130:131], v[242:243], v[66:67] op_sel_hi:[1,0,1]
	v_pk_fma_f32 v[132:133], v[132:133], v[242:243], v[68:69] op_sel_hi:[1,0,1]
	v_pk_mul_f32 v[234:235], v[142:143], s[100:101] op_sel_hi:[1,0]
	v_pk_mul_f32 v[236:237], v[144:145], s[100:101] op_sel_hi:[1,0]
	v_exp_f32_e32 v234, v234
	v_exp_f32_e32 v235, v235
	v_exp_f32_e32 v236, v236
	v_exp_f32_e32 v237, v237
	v_pk_add_f32 v[234:235], v[234:235], 1.0 op_sel_hi:[1,0]
	v_pk_add_f32 v[236:237], v[236:237], 1.0 op_sel_hi:[1,0]
	v_rcp_f32_e32 v234, v234
	v_rcp_f32_e32 v235, v235
	v_rcp_f32_e32 v236, v236
	v_rcp_f32_e32 v237, v237
	v_pk_mul_f32 v[134:135], v[142:143], v[134:135]
	v_pk_mul_f32 v[136:137], v[144:145], v[136:137]
	v_pk_mul_f32 v[134:135], v[134:135], v[234:235]
	v_pk_mul_f32 v[136:137], v[136:137], v[236:237]
	v_cvt_pk_bf16_f32 v238, v134, v135
	v_cvt_pk_bf16_f32 v239, v136, v137
	v_pk_mul_f32 v[234:235], v[138:139], s[100:101] op_sel_hi:[1,0]
	v_pk_mul_f32 v[236:237], v[140:141], s[100:101] op_sel_hi:[1,0]
	v_exp_f32_e32 v234, v234
	v_exp_f32_e32 v235, v235
	v_exp_f32_e32 v236, v236
	v_exp_f32_e32 v237, v237
	v_pk_add_f32 v[234:235], v[234:235], 1.0 op_sel_hi:[1,0]
	v_pk_add_f32 v[236:237], v[236:237], 1.0 op_sel_hi:[1,0]
	v_rcp_f32_e32 v234, v234
	v_rcp_f32_e32 v235, v235
	v_rcp_f32_e32 v236, v236
	v_rcp_f32_e32 v237, v237
	v_pk_mul_f32 v[130:131], v[138:139], v[130:131]
	v_pk_mul_f32 v[132:133], v[140:141], v[132:133]
	v_pk_mul_f32 v[130:131], v[130:131], v[234:235]
	v_pk_mul_f32 v[132:133], v[132:133], v[236:237]
	v_cvt_pk_bf16_f32 v240, v130, v131
	v_cvt_pk_bf16_f32 v241, v132, v133
	global_store_dwordx4 v[166:167], v[238:241], off
	v_or_b32_e32 v131, 16, v180
	v_mad_i64_i32 v[132:133], s[2:3], v131, s46, v[162:163]
	v_lshl_add_u64 v[132:133], v[132:133], 0, v[164:165]
	v_pk_fma_f32 v[126:127], v[126:127], v[244:245], v[78:79] op_sel_hi:[1,0,1]
; __device__ __forceinline__ unsigned cvt_pk_bf16(float lo, float hi) { unsigned r; asm volatile("v_cvt_pk_bf16_f32 %0, %1, %2" : "=v"(r) : "v"(lo), "v"(hi)); return r; }
; __device__ __forceinline__ float silu_mul(float a, float b) { return a * b * __builtin_amdgcn_rcpf(1.0f + __builtin_amdgcn_exp2f(-a * LOG2E)); }
;     __device__ __forceinline__ void operator()(const f32x4 (&acc)[2][2][4][2], const Unit& u, int wr, int wc, int fr, int fq) const {
;     ...
;             for (int m = 0; m < 4; ++m) { const int row = row0 + ai * HALF + m * 16; const float rs = __shfl(ai ? rsl1 : rsl0, m * 16 + fr); bf16_t* rowp = O + (size_t)row * DFF + col0;
;                 const f32x4 a0 = acc[ai][0][m][0] * rs + ba0, a1 = acc[ai][0][m][1] * rs + ba1, b0 = acc[ai][1][m][0] * rs + bb0, b1 = acc[ai][1][m][1] * rs + bb1;
;                 u32x4 w; w.x = cvt_pk_bf16(silu_mul(a0[0], b0[0]), silu_mul(a0[1], b0[1])); w.y = cvt_pk_bf16(silu_mul(a0[2], b0[2]), silu_mul(a0[3], b0[3]));
;                 w.z = cvt_pk_bf16(silu_mul(a1[0], b1[0]), silu_mul(a1[1], b1[1])); w.w = cvt_pk_bf16(silu_mul(a1[2], b1[2]), silu_mul(a1[3], b1[3]));
;                 *(u32x4*)rowp = w; }
	v_pk_fma_f32 v[128:129], v[128:129], v[244:245], v[80:81] op_sel_hi:[1,0,1]
	v_pk_fma_f32 v[118:119], v[118:119], v[244:245], v[70:71] op_sel_hi:[1,0,1]
	v_pk_fma_f32 v[120:121], v[120:121], v[244:245], v[72:73] op_sel_hi:[1,0,1]
	v_pk_fma_f32 v[122:123], v[122:123], v[244:245], v[74:75] op_sel_hi:[1,0,1]
	v_pk_fma_f32 v[124:125], v[124:125], v[244:245], v[76:77] op_sel_hi:[1,0,1]
	v_pk_fma_f32 v[114:115], v[114:115], v[244:245], v[66:67] op_sel_hi:[1,0,1]
	v_pk_fma_f32 v[116:117], v[116:117], v[244:245], v[68:69] op_sel_hi:[1,0,1]
	v_pk_mul_f32 v[234:235], v[126:127], s[100:101] op_sel_hi:[1,0]
	v_pk_mul_f32 v[236:237], v[128:129], s[100:101] op_sel_hi:[1,0]
	v_exp_f32_e32 v234, v234
	v_exp_f32_e32 v235, v235
	v_exp_f32_e32 v236, v236
	v_exp_f32_e32 v237, v237
	v_pk_add_f32 v[234:235], v[234:235], 1.0 op_sel_hi:[1,0]
	v_pk_add_f32 v[236:237], v[236:237], 1.0 op_sel_hi:[1,0]
	v_rcp_f32_e32 v234, v234
	v_rcp_f32_e32 v235, v235
	v_rcp_f32_e32 v236, v236
	v_rcp_f32_e32 v237, v237
	v_pk_mul_f32 v[118:119], v[126:127], v[118:119]
	v_pk_mul_f32 v[120:121], v[128:129], v[120:121]
	v_pk_mul_f32 v[118:119], v[118:119], v[234:235]
	v_pk_mul_f32 v[120:121], v[120:121], v[236:237]
	v_cvt_pk_bf16_f32 v238, v118, v119
	v_cvt_pk_bf16_f32 v239, v120, v121
	v_pk_mul_f32 v[234:235], v[122:123], s[100:101] op_sel_hi:[1,0]
	v_pk_mul_f32 v[236:237], v[124:125], s[100:101] op_sel_hi:[1,0]
	v_exp_f32_e32 v234, v234
	v_exp_f32_e32 v235, v235
	v_exp_f32_e32 v236, v236
	v_exp_f32_e32 v237, v237
	v_pk_add_f32 v[234:235], v[234:235], 1.0 op_sel_hi:[1,0]
	v_pk_add_f32 v[236:237], v[236:237], 1.0 op_sel_hi:[1,0]
	v_rcp_f32_e32 v234, v234
	v_rcp_f32_e32 v235, v235
	v_rcp_f32_e32 v236, v236
	v_rcp_f32_e32 v237, v237
	v_pk_mul_f32 v[114:115], v[122:123], v[114:115]
	v_pk_mul_f32 v[116:117], v[124:125], v[116:117]
	v_pk_mul_f32 v[114:115], v[114:115], v[234:235]
	v_pk_mul_f32 v[116:117], v[116:117], v[236:237]
	v_cvt_pk_bf16_f32 v240, v114, v115
	v_cvt_pk_bf16_f32 v241, v116, v117
	global_store_dwordx4 v[132:133], v[238:241], off
	v_or_b32_e32 v115, 32, v180
	v_mad_i64_i32 v[116:117], s[2:3], v115, s46, v[162:163]
	v_lshl_add_u64 v[116:117], v[116:117], 0, v[164:165]
	v_pk_fma_f32 v[110:111], v[110:111], v[246:247], v[78:79] op_sel_hi:[1,0,1]
	v_pk_fma_f32 v[112:113], v[112:113], v[246:247], v[80:81] op_sel_hi:[1,0,1]
	v_pk_fma_f32 v[102:103], v[102:103], v[246:247], v[70:71] op_sel_hi:[1,0,1]
	v_pk_fma_f32 v[104:105], v[104:105], v[246:247], v[72:73] op_sel_hi:[1,0,1]
	v_pk_fma_f32 v[106:107], v[106:107], v[246:247], v[74:75] op_sel_hi:[1,0,1]
	v_pk_fma_f32 v[108:109], v[108:109], v[246:247], v[76:77] op_sel_hi:[1,0,1]
	v_pk_fma_f32 v[98:99], v[98:99], v[246:247], v[66:67] op_sel_hi:[1,0,1]
	v_pk_fma_f32 v[100:101], v[100:101], v[246:247], v[68:69] op_sel_hi:[1,0,1]
	v_pk_mul_f32 v[234:235], v[110:111], s[100:101] op_sel_hi:[1,0]
	v_pk_mul_f32 v[236:237], v[112:113], s[100:101] op_sel_hi:[1,0]
	v_exp_f32_e32 v234, v234
	v_exp_f32_e32 v235, v235
	v_exp_f32_e32 v236, v236
	v_exp_f32_e32 v237, v237
	v_pk_add_f32 v[234:235], v[234:235], 1.0 op_sel_hi:[1,0]
	v_pk_add_f32 v[236:237], v[236:237], 1.0 op_sel_hi:[1,0]
	v_rcp_f32_e32 v234, v234
	v_rcp_f32_e32 v235, v235
	v_rcp_f32_e32 v236, v236
	v_rcp_f32_e32 v237, v237
	v_pk_mul_f32 v[102:103], v[110:111], v[102:103]
	v_pk_mul_f32 v[104:105], v[112:113], v[104:105]
	v_pk_mul_f32 v[102:103], v[102:103], v[234:235]
	v_pk_mul_f32 v[104:105], v[104:105], v[236:237]
	v_cvt_pk_bf16_f32 v238, v102, v103
	v_cvt_pk_bf16_f32 v239, v104, v105
	v_pk_mul_f32 v[234:235], v[106:107], s[100:101] op_sel_hi:[1,0]
	v_pk_mul_f32 v[236:237], v[108:109], s[100:101] op_sel_hi:[1,0]
	v_exp_f32_e32 v234, v234
	v_exp_f32_e32 v235, v235
	v_exp_f32_e32 v236, v236
	v_exp_f32_e32 v237, v237
	v_pk_add_f32 v[234:235], v[234:235], 1.0 op_sel_hi:[1,0]
	v_pk_add_f32 v[236:237], v[236:237], 1.0 op_sel_hi:[1,0]
	v_rcp_f32_e32 v234, v234
	v_rcp_f32_e32 v235, v235
	v_rcp_f32_e32 v236, v236
	v_rcp_f32_e32 v237, v237
	v_pk_mul_f32 v[98:99], v[106:107], v[98:99]
	v_pk_mul_f32 v[100:101], v[108:109], v[100:101]
	v_pk_mul_f32 v[98:99], v[98:99], v[234:235]
	v_pk_mul_f32 v[100:101], v[100:101], v[236:237]
	v_cvt_pk_bf16_f32 v240, v98, v99
	v_cvt_pk_bf16_f32 v241, v100, v101
	global_store_dwordx4 v[116:117], v[238:241], off
	v_or_b32_e32 v99, 48, v180
	v_mad_i64_i32 v[100:101], s[2:3], v99, s46, v[162:163]
	v_lshl_add_u64 v[100:101], v[100:101], 0, v[164:165]
	v_pk_fma_f32 v[94:95], v[94:95], v[248:249], v[78:79] op_sel_hi:[1,0,1]
	v_pk_fma_f32 v[96:97], v[96:97], v[248:249], v[80:81] op_sel_hi:[1,0,1]
	v_pk_fma_f32 v[86:87], v[86:87], v[248:249], v[70:71] op_sel_hi:[1,0,1]
	v_pk_fma_f32 v[88:89], v[88:89], v[248:249], v[72:73] op_sel_hi:[1,0,1]
	v_pk_fma_f32 v[90:91], v[90:91], v[248:249], v[74:75] op_sel_hi:[1,0,1]
	v_pk_fma_f32 v[92:93], v[92:93], v[248:249], v[76:77] op_sel_hi:[1,0,1]
	v_pk_fma_f32 v[82:83], v[82:83], v[248:249], v[66:67] op_sel_hi:[1,0,1]
	v_pk_fma_f32 v[84:85], v[84:85], v[248:249], v[68:69] op_sel_hi:[1,0,1]
	v_pk_mul_f32 v[234:235], v[94:95], s[100:101] op_sel_hi:[1,0]
	v_pk_mul_f32 v[236:237], v[96:97], s[100:101] op_sel_hi:[1,0]
	v_exp_f32_e32 v234, v234
	v_exp_f32_e32 v235, v235
	v_exp_f32_e32 v236, v236
	v_exp_f32_e32 v237, v237
	v_pk_add_f32 v[234:235], v[234:235], 1.0 op_sel_hi:[1,0]
	v_pk_add_f32 v[236:237], v[236:237], 1.0 op_sel_hi:[1,0]
	v_rcp_f32_e32 v234, v234
	v_rcp_f32_e32 v235, v235
	v_rcp_f32_e32 v236, v236
	v_rcp_f32_e32 v237, v237
	v_pk_mul_f32 v[86:87], v[94:95], v[86:87]
	v_pk_mul_f32 v[88:89], v[96:97], v[88:89]
	v_pk_mul_f32 v[86:87], v[86:87], v[234:235]
	v_pk_mul_f32 v[88:89], v[88:89], v[236:237]
	v_cvt_pk_bf16_f32 v238, v86, v87
; __device__ __forceinline__ unsigned cvt_pk_bf16(float lo, float hi) { unsigned r; asm volatile("v_cvt_pk_bf16_f32 %0, %1, %2" : "=v"(r) : "v"(lo), "v"(hi)); return r; }
; __device__ __forceinline__ float row_rstd(const float* ss, int row) { return 1.0f / sqrtf(ss[row] * (1.0f / DM) + 1e-6f); }
; __device__ __forceinline__ float silu_mul(float a, float b) { return a * b * __builtin_amdgcn_rcpf(1.0f + __builtin_amdgcn_exp2f(-a * LOG2E)); }
;     __device__ __forceinline__ void operator()(const f32x4 (&acc)[2][2][4][2], const Unit& u, int wr, int wc, int fr, int fq) const {
;     ...
;         const float rsl0 = row_rstd(ss, u.pm * BM + wr * 64 + lane), rsl1 = row_rstd(ss, u.pm * BM + HALF + wr * 64 + lane);
; #pragma unroll
;         for (int ai = 0; ai < 2; ++ai)
; #pragma unroll
;             for (int m = 0; m < 4; ++m) { const int row = row0 + ai * HALF + m * 16; const float rs = __shfl(ai ? rsl1 : rsl0, m * 16 + fr); bf16_t* rowp = O + (size_t)row * DFF + col0;
;                 const f32x4 a0 = acc[ai][0][m][0] * rs + ba0, a1 = acc[ai][0][m][1] * rs + ba1, b0 = acc[ai][1][m][0] * rs + bb0, b1 = acc[ai][1][m][1] * rs + bb1;
;                 u32x4 w; w.x = cvt_pk_bf16(silu_mul(a0[0], b0[0]), silu_mul(a0[1], b0[1])); w.y = cvt_pk_bf16(silu_mul(a0[2], b0[2]), silu_mul(a0[3], b0[3]));
;                 w.z = cvt_pk_bf16(silu_mul(a1[0], b1[0]), silu_mul(a1[1], b1[1])); w.w = cvt_pk_bf16(silu_mul(a1[2], b1[2]), silu_mul(a1[3], b1[3]));
;                 *(u32x4*)rowp = w; }
	v_cvt_pk_bf16_f32 v239, v88, v89
	v_pk_mul_f32 v[234:235], v[90:91], s[100:101] op_sel_hi:[1,0]
	v_pk_mul_f32 v[236:237], v[92:93], s[100:101] op_sel_hi:[1,0]
	v_exp_f32_e32 v234, v234
	v_exp_f32_e32 v235, v235
	v_exp_f32_e32 v236, v236
	v_exp_f32_e32 v237, v237
	v_pk_add_f32 v[234:235], v[234:235], 1.0 op_sel_hi:[1,0]
	v_pk_add_f32 v[236:237], v[236:237], 1.0 op_sel_hi:[1,0]
	v_rcp_f32_e32 v234, v234
	v_rcp_f32_e32 v235, v235
	v_rcp_f32_e32 v236, v236
	v_rcp_f32_e32 v237, v237
	v_pk_mul_f32 v[82:83], v[90:91], v[82:83]
	v_pk_mul_f32 v[84:85], v[92:93], v[84:85]
	v_pk_mul_f32 v[82:83], v[82:83], v[234:235]
	v_pk_mul_f32 v[84:85], v[84:85], v[236:237]
	v_cvt_pk_bf16_f32 v240, v82, v83
	v_cvt_pk_bf16_f32 v241, v84, v85
	global_store_dwordx4 v[100:101], v[238:241], off
	s_nop 1
	v_div_scale_f32 v82, s[2:3], v181, v181, 1.0
	v_rcp_f32_e32 v84, v82
	v_add_u32_e32 v83, 0x80, v180
	v_fma_f32 v85, -v82, v84, 1.0
	v_fmac_f32_e32 v84, v85, v84
	v_div_scale_f32 v85, vcc, 1.0, v181, 1.0
	v_mul_f32_e32 v86, v85, v84
	v_fma_f32 v87, -v82, v86, v85
	v_fmac_f32_e32 v86, v87, v84
	v_fma_f32 v82, -v82, v86, v85
	v_div_fmas_f32 v82, v82, v84, v86
	v_div_fixup_f32 v82, v82, v181, 1.0
	ds_bpermute_b32 v242, v179, v82
	ds_bpermute_b32 v244, v179, v82 offset:64
	ds_bpermute_b32 v246, v179, v82 offset:128
	ds_bpermute_b32 v248, v179, v82 offset:192
	v_mad_i64_i32 v[86:87], s[2:3], v83, s46, v[162:163]
	v_lshl_add_u64 v[86:87], v[86:87], 0, v[164:165]
	s_and_b64 vcc, s[38:39], exec
	s_waitcnt lgkmcnt(0)
	v_pk_fma_f32 v[62:63], v[62:63], v[242:243], v[78:79] op_sel_hi:[1,0,1]
	v_pk_fma_f32 v[64:65], v[64:65], v[242:243], v[80:81] op_sel_hi:[1,0,1]
	v_pk_fma_f32 v[54:55], v[54:55], v[242:243], v[70:71] op_sel_hi:[1,0,1]
	v_pk_fma_f32 v[56:57], v[56:57], v[242:243], v[72:73] op_sel_hi:[1,0,1]
	v_pk_fma_f32 v[58:59], v[58:59], v[242:243], v[74:75] op_sel_hi:[1,0,1]
	v_pk_fma_f32 v[60:61], v[60:61], v[242:243], v[76:77] op_sel_hi:[1,0,1]
	v_pk_fma_f32 v[50:51], v[50:51], v[242:243], v[66:67] op_sel_hi:[1,0,1]
	v_pk_fma_f32 v[52:53], v[52:53], v[242:243], v[68:69] op_sel_hi:[1,0,1]
	v_pk_mul_f32 v[234:235], v[62:63], s[100:101] op_sel_hi:[1,0]
	v_pk_mul_f32 v[236:237], v[64:65], s[100:101] op_sel_hi:[1,0]
	v_exp_f32_e32 v234, v234
	v_exp_f32_e32 v235, v235
	v_exp_f32_e32 v236, v236
	v_exp_f32_e32 v237, v237
	v_pk_add_f32 v[234:235], v[234:235], 1.0 op_sel_hi:[1,0]
	v_pk_add_f32 v[236:237], v[236:237], 1.0 op_sel_hi:[1,0]
	v_rcp_f32_e32 v234, v234
	v_rcp_f32_e32 v235, v235
	v_rcp_f32_e32 v236, v236
	v_rcp_f32_e32 v237, v237
	v_pk_mul_f32 v[54:55], v[62:63], v[54:55]
	v_pk_mul_f32 v[56:57], v[64:65], v[56:57]
	v_pk_mul_f32 v[54:55], v[54:55], v[234:235]
	v_pk_mul_f32 v[56:57], v[56:57], v[236:237]
	v_cvt_pk_bf16_f32 v238, v54, v55
	v_cvt_pk_bf16_f32 v239, v56, v57
	v_pk_mul_f32 v[234:235], v[58:59], s[100:101] op_sel_hi:[1,0]
	v_pk_mul_f32 v[236:237], v[60:61], s[100:101] op_sel_hi:[1,0]
	v_exp_f32_e32 v234, v234
	v_exp_f32_e32 v235, v235
	v_exp_f32_e32 v236, v236
	v_exp_f32_e32 v237, v237
	v_pk_add_f32 v[234:235], v[234:235], 1.0 op_sel_hi:[1,0]
	v_pk_add_f32 v[236:237], v[236:237], 1.0 op_sel_hi:[1,0]
	v_rcp_f32_e32 v234, v234
	v_rcp_f32_e32 v235, v235
	v_rcp_f32_e32 v236, v236
	v_rcp_f32_e32 v237, v237
	v_pk_mul_f32 v[50:51], v[58:59], v[50:51]
	v_pk_mul_f32 v[52:53], v[60:61], v[52:53]
	v_pk_mul_f32 v[50:51], v[50:51], v[234:235]
	v_pk_mul_f32 v[52:53], v[52:53], v[236:237]
	v_cvt_pk_bf16_f32 v240, v50, v51
	v_cvt_pk_bf16_f32 v241, v52, v53
	global_store_dwordx4 v[86:87], v[238:241], off
	v_add_u32_e32 v51, 0x90, v180
	v_mad_i64_i32 v[52:53], s[2:3], v51, s46, v[162:163]
	v_lshl_add_u64 v[52:53], v[52:53], 0, v[164:165]
	v_pk_fma_f32 v[46:47], v[46:47], v[244:245], v[78:79] op_sel_hi:[1,0,1]
	v_pk_fma_f32 v[48:49], v[48:49], v[244:245], v[80:81] op_sel_hi:[1,0,1]
	v_pk_fma_f32 v[38:39], v[38:39], v[244:245], v[70:71] op_sel_hi:[1,0,1]
	v_pk_fma_f32 v[40:41], v[40:41], v[244:245], v[72:73] op_sel_hi:[1,0,1]
	v_pk_fma_f32 v[42:43], v[42:43], v[244:245], v[74:75] op_sel_hi:[1,0,1]
	v_pk_fma_f32 v[44:45], v[44:45], v[244:245], v[76:77] op_sel_hi:[1,0,1]
	v_pk_fma_f32 v[34:35], v[34:35], v[244:245], v[66:67] op_sel_hi:[1,0,1]
	v_pk_fma_f32 v[36:37], v[36:37], v[244:245], v[68:69] op_sel_hi:[1,0,1]
	v_pk_mul_f32 v[234:235], v[46:47], s[100:101] op_sel_hi:[1,0]
	v_pk_mul_f32 v[236:237], v[48:49], s[100:101] op_sel_hi:[1,0]
	v_exp_f32_e32 v234, v234
	v_exp_f32_e32 v235, v235
	v_exp_f32_e32 v236, v236
	v_exp_f32_e32 v237, v237
	v_pk_add_f32 v[234:235], v[234:235], 1.0 op_sel_hi:[1,0]
	v_pk_add_f32 v[236:237], v[236:237], 1.0 op_sel_hi:[1,0]
	v_rcp_f32_e32 v234, v234
	v_rcp_f32_e32 v235, v235
	v_rcp_f32_e32 v236, v236
	v_rcp_f32_e32 v237, v237
	v_pk_mul_f32 v[38:39], v[46:47], v[38:39]
	v_pk_mul_f32 v[40:41], v[48:49], v[40:41]
	v_pk_mul_f32 v[38:39], v[38:39], v[234:235]
	v_pk_mul_f32 v[40:41], v[40:41], v[236:237]
	v_cvt_pk_bf16_f32 v238, v38, v39
	v_cvt_pk_bf16_f32 v239, v40, v41
	v_pk_mul_f32 v[234:235], v[42:43], s[100:101] op_sel_hi:[1,0]
	v_pk_mul_f32 v[236:237], v[44:45], s[100:101] op_sel_hi:[1,0]
; __device__ __forceinline__ unsigned cvt_pk_bf16(float lo, float hi) { unsigned r; asm volatile("v_cvt_pk_bf16_f32 %0, %1, %2" : "=v"(r) : "v"(lo), "v"(hi)); return r; }
; __device__ __forceinline__ float silu_mul(float a, float b) { return a * b * __builtin_amdgcn_rcpf(1.0f + __builtin_amdgcn_exp2f(-a * LOG2E)); }
; #define PG8_BAR __builtin_amdgcn_s_barrier()
;     __device__ __forceinline__ void operator()(const f32x4 (&acc)[2][2][4][2], const Unit& u, int wr, int wc, int fr, int fq) const {
;     ...
;             for (int m = 0; m < 4; ++m) { const int row = row0 + ai * HALF + m * 16; const float rs = __shfl(ai ? rsl1 : rsl0, m * 16 + fr); bf16_t* rowp = O + (size_t)row * DFF + col0;
;                 const f32x4 a0 = acc[ai][0][m][0] * rs + ba0, a1 = acc[ai][0][m][1] * rs + ba1, b0 = acc[ai][1][m][0] * rs + bb0, b1 = acc[ai][1][m][1] * rs + bb1;
;                 u32x4 w; w.x = cvt_pk_bf16(silu_mul(a0[0], b0[0]), silu_mul(a0[1], b0[1])); w.y = cvt_pk_bf16(silu_mul(a0[2], b0[2]), silu_mul(a0[3], b0[3]));
;                 w.z = cvt_pk_bf16(silu_mul(a1[0], b1[0]), silu_mul(a1[1], b1[1])); w.w = cvt_pk_bf16(silu_mul(a1[2], b1[2]), silu_mul(a1[3], b1[3]));
;                 *(u32x4*)rowp = w; }
; template <class Epi, class Sched, bool ALIGN_EPI = false, bool SP2 = false>
; __device__ __forceinline__ void gemm_phase(LAS unsigned char* lds, const Gemm g, const Sched& S, const Epi& E) {
;     ...
;         if constexpr (!Epi::AFTER_DRAIN) { E(acc, cur, wr, wc, fr, fq); S.done(cur); }
;         if (!has_next) break;
; #pragma unroll
;         for (int a = 0; a < 2; ++a)
; #pragma unroll
;             for (int b = 0; b < 2; ++b)
; #pragma unroll
;                 for (int m = 0; m < 4; ++m)
; #pragma unroll
;                     for (int n = 0; n < 2; ++n) acc[a][b][m][n] = (f32x4){0.f, 0.f, 0.f, 0.f};
;         cur = nxt; cA = nA; cB = nB; ++ui;
;         if constexpr (ALIGN_EPI) { if (wr == 1) PG8_BAR; }
	v_exp_f32_e32 v234, v234
	v_exp_f32_e32 v235, v235
	v_exp_f32_e32 v236, v236
	v_exp_f32_e32 v237, v237
	v_pk_add_f32 v[234:235], v[234:235], 1.0 op_sel_hi:[1,0]
	v_pk_add_f32 v[236:237], v[236:237], 1.0 op_sel_hi:[1,0]
	v_rcp_f32_e32 v234, v234
	v_rcp_f32_e32 v235, v235
	v_rcp_f32_e32 v236, v236
	v_rcp_f32_e32 v237, v237
	v_pk_mul_f32 v[34:35], v[42:43], v[34:35]
	v_pk_mul_f32 v[36:37], v[44:45], v[36:37]
	v_pk_mul_f32 v[34:35], v[34:35], v[234:235]
	v_pk_mul_f32 v[36:37], v[36:37], v[236:237]
	v_cvt_pk_bf16_f32 v240, v34, v35
	v_cvt_pk_bf16_f32 v241, v36, v37
	global_store_dwordx4 v[52:53], v[238:241], off
	v_add_u32_e32 v35, 0xa0, v180
	v_mad_i64_i32 v[36:37], s[2:3], v35, s46, v[162:163]
	v_lshl_add_u64 v[36:37], v[36:37], 0, v[164:165]
	v_pk_fma_f32 v[30:31], v[30:31], v[246:247], v[78:79] op_sel_hi:[1,0,1]
	v_pk_fma_f32 v[32:33], v[32:33], v[246:247], v[80:81] op_sel_hi:[1,0,1]
	v_pk_fma_f32 v[22:23], v[22:23], v[246:247], v[70:71] op_sel_hi:[1,0,1]
	v_pk_fma_f32 v[24:25], v[24:25], v[246:247], v[72:73] op_sel_hi:[1,0,1]
	v_pk_fma_f32 v[26:27], v[26:27], v[246:247], v[74:75] op_sel_hi:[1,0,1]
	v_pk_fma_f32 v[28:29], v[28:29], v[246:247], v[76:77] op_sel_hi:[1,0,1]
	v_pk_fma_f32 v[18:19], v[18:19], v[246:247], v[66:67] op_sel_hi:[1,0,1]
	v_pk_fma_f32 v[20:21], v[20:21], v[246:247], v[68:69] op_sel_hi:[1,0,1]
	v_pk_mul_f32 v[234:235], v[30:31], s[100:101] op_sel_hi:[1,0]
	v_pk_mul_f32 v[236:237], v[32:33], s[100:101] op_sel_hi:[1,0]
	v_exp_f32_e32 v234, v234
	v_exp_f32_e32 v235, v235
	v_exp_f32_e32 v236, v236
	v_exp_f32_e32 v237, v237
	v_pk_add_f32 v[234:235], v[234:235], 1.0 op_sel_hi:[1,0]
	v_pk_add_f32 v[236:237], v[236:237], 1.0 op_sel_hi:[1,0]
	v_rcp_f32_e32 v234, v234
	v_rcp_f32_e32 v235, v235
	v_rcp_f32_e32 v236, v236
	v_rcp_f32_e32 v237, v237
	v_pk_mul_f32 v[22:23], v[30:31], v[22:23]
	v_pk_mul_f32 v[24:25], v[32:33], v[24:25]
	v_pk_mul_f32 v[22:23], v[22:23], v[234:235]
	v_pk_mul_f32 v[24:25], v[24:25], v[236:237]
	v_cvt_pk_bf16_f32 v238, v22, v23
	v_cvt_pk_bf16_f32 v239, v24, v25
	v_pk_mul_f32 v[234:235], v[26:27], s[100:101] op_sel_hi:[1,0]
	v_pk_mul_f32 v[236:237], v[28:29], s[100:101] op_sel_hi:[1,0]
	v_exp_f32_e32 v234, v234
	v_exp_f32_e32 v235, v235
	v_exp_f32_e32 v236, v236
	v_exp_f32_e32 v237, v237
	v_pk_add_f32 v[234:235], v[234:235], 1.0 op_sel_hi:[1,0]
	v_pk_add_f32 v[236:237], v[236:237], 1.0 op_sel_hi:[1,0]
	v_rcp_f32_e32 v234, v234
	v_rcp_f32_e32 v235, v235
	v_rcp_f32_e32 v236, v236
	v_rcp_f32_e32 v237, v237
	v_pk_mul_f32 v[18:19], v[26:27], v[18:19]
	v_pk_mul_f32 v[20:21], v[28:29], v[20:21]
	v_pk_mul_f32 v[18:19], v[18:19], v[234:235]
	v_pk_mul_f32 v[20:21], v[20:21], v[236:237]
	v_cvt_pk_bf16_f32 v240, v18, v19
	v_cvt_pk_bf16_f32 v241, v20, v21
	global_store_dwordx4 v[36:37], v[238:241], off
	v_add_u32_e32 v19, 0xb0, v180
	v_mad_i64_i32 v[20:21], s[2:3], v19, s46, v[162:163]
	v_lshl_add_u64 v[20:21], v[20:21], 0, v[164:165]
	s_mov_b64 s[2:3], -1
	v_pk_fma_f32 v[14:15], v[14:15], v[248:249], v[78:79] op_sel_hi:[1,0,1]
	v_pk_fma_f32 v[16:17], v[16:17], v[248:249], v[80:81] op_sel_hi:[1,0,1]
	v_pk_fma_f32 v[6:7], v[6:7], v[248:249], v[70:71] op_sel_hi:[1,0,1]
	v_pk_fma_f32 v[8:9], v[8:9], v[248:249], v[72:73] op_sel_hi:[1,0,1]
	v_pk_fma_f32 v[10:11], v[10:11], v[248:249], v[74:75] op_sel_hi:[1,0,1]
	v_pk_fma_f32 v[12:13], v[12:13], v[248:249], v[76:77] op_sel_hi:[1,0,1]
	v_pk_fma_f32 v[2:3], v[2:3], v[248:249], v[66:67] op_sel_hi:[1,0,1]
	v_pk_fma_f32 v[4:5], v[4:5], v[248:249], v[68:69] op_sel_hi:[1,0,1]
	v_pk_mul_f32 v[234:235], v[14:15], s[100:101] op_sel_hi:[1,0]
	v_pk_mul_f32 v[236:237], v[16:17], s[100:101] op_sel_hi:[1,0]
	v_exp_f32_e32 v234, v234
	v_exp_f32_e32 v235, v235
	v_exp_f32_e32 v236, v236
	v_exp_f32_e32 v237, v237
	v_pk_add_f32 v[234:235], v[234:235], 1.0 op_sel_hi:[1,0]
	v_pk_add_f32 v[236:237], v[236:237], 1.0 op_sel_hi:[1,0]
	v_rcp_f32_e32 v234, v234
	v_rcp_f32_e32 v235, v235
	v_rcp_f32_e32 v236, v236
	v_rcp_f32_e32 v237, v237
	v_pk_mul_f32 v[6:7], v[14:15], v[6:7]
	v_pk_mul_f32 v[8:9], v[16:17], v[8:9]
	v_pk_mul_f32 v[6:7], v[6:7], v[234:235]
	v_pk_mul_f32 v[8:9], v[8:9], v[236:237]
	v_cvt_pk_bf16_f32 v238, v6, v7
	v_cvt_pk_bf16_f32 v239, v8, v9
	v_pk_mul_f32 v[234:235], v[10:11], s[100:101] op_sel_hi:[1,0]
	v_pk_mul_f32 v[236:237], v[12:13], s[100:101] op_sel_hi:[1,0]
	v_exp_f32_e32 v234, v234
	v_exp_f32_e32 v235, v235
	v_exp_f32_e32 v236, v236
	v_exp_f32_e32 v237, v237
	v_pk_add_f32 v[234:235], v[234:235], 1.0 op_sel_hi:[1,0]
	v_pk_add_f32 v[236:237], v[236:237], 1.0 op_sel_hi:[1,0]
	v_rcp_f32_e32 v234, v234
	v_rcp_f32_e32 v235, v235
	v_rcp_f32_e32 v236, v236
	v_rcp_f32_e32 v237, v237
	v_pk_mul_f32 v[2:3], v[10:11], v[2:3]
	v_pk_mul_f32 v[4:5], v[12:13], v[4:5]
	v_pk_mul_f32 v[2:3], v[2:3], v[234:235]
	v_pk_mul_f32 v[4:5], v[4:5], v[236:237]
	v_cvt_pk_bf16_f32 v240, v2, v3
	v_cvt_pk_bf16_f32 v241, v4, v5
	global_store_dwordx4 v[20:21], v[238:241], off
	s_waitcnt vmcnt(8)
	s_cbranch_vccz .LBB0_1818
	s_andn2_b64 vcc, exec, s[4:5]
	s_cbranch_vccnz .LBB0_1817
	s_barrier
	s_branch .LBB0_1817

; __device__ __forceinline__ unsigned cvt_pk_bf16(float lo, float hi) { unsigned r; asm volatile("v_cvt_pk_bf16_f32 %0, %1, %2" : "=v"(r) : "v"(lo), "v"(hi)); return r; }
; __device__ __forceinline__ float silu_mul(float a, float b) { return a * b * __builtin_amdgcn_rcpf(1.0f + __builtin_amdgcn_exp2f(-a * LOG2E)); }
; __device__ __forceinline__ float row_rstd(const float* ss, int row) { return 1.0f / sqrtf(ss[row] * (1.0f / DM) + 1e-6f); }
;     __device__ __forceinline__ void operator()(const f32x4 (&acc)[2][2][4][2], const Unit& u, int wr, int wc, int fr, int fq) const {
;         const int row0 = u.pm * BM + wr * 64 + fr, col0 = u.pn * HALF + wc * 32 + 8 * fq;
;         const int s = (u.pm < ML / BM) ? (u.pm >> 5) : 4;
;         const float* bp = bias + (size_t)s * BIAS_N + u.pn * BM + wc * 32 + 8 * fq;
;         const f32x4 ba0 = *(const f32x4*)bp, ba1 = *(const f32x4*)(bp + 4), bb0 = *(const f32x4*)(bp + HALF), bb1 = *(const f32x4*)(bp + HALF + 4);
;         const int lane = fq * 16 + fr;
;         const float rsl0 = row_rstd(ss, u.pm * BM + wr * 64 + lane), rsl1 = row_rstd(ss, u.pm * BM + HALF + wr * 64 + lane);
; #pragma unroll
;         for (int ai = 0; ai < 2; ++ai)
; #pragma unroll
;             for (int m = 0; m < 4; ++m) { const int row = row0 + ai * HALF + m * 16; const float rs = __shfl(ai ? rsl1 : rsl0, m * 16 + fr); bf16_t* rowp = O + (size_t)row * DFF + col0;
;                 const f32x4 a0 = acc[ai][0][m][0] * rs + ba0, a1 = acc[ai][0][m][1] * rs + ba1, b0 = acc[ai][1][m][0] * rs + bb0, b1 = acc[ai][1][m][1] * rs + bb1;
;                 u32x4 w; w.x = cvt_pk_bf16(silu_mul(a0[0], b0[0]), silu_mul(a0[1], b0[1])); w.y = cvt_pk_bf16(silu_mul(a0[2], b0[2]), silu_mul(a0[3], b0[3]));
;                 w.z = cvt_pk_bf16(silu_mul(a1[0], b1[0]), silu_mul(a1[1], b1[1])); w.w = cvt_pk_bf16(silu_mul(a1[2], b1[2]), silu_mul(a1[3], b1[3]));
;                 *(u32x4*)rowp = w; }
.LBB0_2921:
	s_lshl_b32 s2, s2, 8
	s_add_i32 s11, s2, s34
	s_lshl_b64 s[18:19], s[18:19], 2
	s_add_u32 s13, s35, s18
	s_addc_u32 s18, s38, s19
	s_lshl_b32 s2, s3, 8
	v_lshl_or_b32 v164, s3, 7, v172
	s_ashr_i32 s3, s2, 31
	s_lshl_b64 s[2:3], s[2:3], 2
	s_add_u32 s2, s13, s2
	s_addc_u32 s3, s18, s3
	v_or_b32_e32 v162, s11, v170
	s_add_u32 s2, s2, s44
	v_ashrrev_i32_e32 v163, 31, v162
	s_addc_u32 s3, s3, 0
	v_lshl_add_u64 v[162:163], v[162:163], 2, s[0:1]
	v_mov_b32_e32 v74, v234
	v_mov_b32_e32 v75, v235
	v_mov_b32_e32 v76, v236
	v_mov_b32_e32 v77, v237
	v_mov_b32_e32 v78, v238
	v_mov_b32_e32 v79, v239
	v_mov_b32_e32 v80, v240
	v_mov_b32_e32 v81, v241
	v_mov_b32_e32 v66, v242
	v_mov_b32_e32 v67, v243
	v_mov_b32_e32 v68, v244
	v_mov_b32_e32 v69, v245
	v_mov_b32_e32 v70, v246
	v_mov_b32_e32 v71, v247
	v_mov_b32_e32 v72, v248
	v_mov_b32_e32 v73, v249
	v_or_b32_e32 v180, s11, v1
	v_mov_b32_e32 v162, v250
	v_fmamk_f32 v162, v162, 0x3a000000, v177
	v_cmp_gt_f32_e32 vcc, s45, v162
	v_mul_f32_e32 v163, 0x4f800000, v162
	s_nop 0
	v_cndmask_b32_e32 v162, v162, v163, vcc
	v_sqrt_f32_e32 v163, v162
	s_nop 0
	v_add_u32_e32 v165, -1, v163
	v_fma_f32 v166, -v165, v163, v162
	v_cmp_ge_f32_e64 s[2:3], 0, v166
	v_add_u32_e32 v166, 1, v163
	s_nop 0
	v_cndmask_b32_e64 v165, v163, v165, s[2:3]
	v_fma_f32 v163, -v166, v163, v162
	v_cmp_lt_f32_e64 s[2:3], 0, v163
	s_nop 1
	v_cndmask_b32_e64 v163, v165, v166, s[2:3]
	v_mul_f32_e32 v165, 0x37800000, v163
	v_cndmask_b32_e32 v163, v163, v165, vcc
	v_cmp_class_f32_e32 vcc, v162, v178
	s_nop 1
	v_cndmask_b32_e32 v166, v163, v162, vcc
	v_add_u32_e32 v162, s11, v171
	v_ashrrev_i32_e32 v163, 31, v162
	v_lshl_add_u64 v[162:163], v[162:163], 2, s[0:1]
	v_mov_b32_e32 v162, v251
	v_fmamk_f32 v162, v162, 0x3a000000, v177
	v_cmp_gt_f32_e32 vcc, s45, v162
	v_mul_f32_e32 v163, 0x4f800000, v162
	s_nop 0
	v_cndmask_b32_e32 v162, v162, v163, vcc
	v_sqrt_f32_e32 v163, v162
	s_nop 0
	v_add_u32_e32 v165, -1, v163
	v_fma_f32 v167, -v165, v163, v162
	v_cmp_ge_f32_e64 s[2:3], 0, v167
	v_add_u32_e32 v167, 1, v163
	s_nop 0
	v_cndmask_b32_e64 v165, v163, v165, s[2:3]
	v_fma_f32 v163, -v167, v163, v162
	v_cmp_lt_f32_e64 s[2:3], 0, v163
	s_nop 1
	v_cndmask_b32_e64 v163, v165, v167, s[2:3]
	v_mul_f32_e32 v165, 0x37800000, v163
	v_cndmask_b32_e32 v163, v163, v165, vcc
	v_cmp_class_f32_e32 vcc, v162, v178
	v_ashrrev_i32_e32 v165, 31, v164
	v_lshlrev_b64 v[164:165], 1, v[164:165]
	v_cndmask_b32_e32 v181, v163, v162, vcc
	v_div_scale_f32 v162, s[2:3], v166, v166, 1.0
	v_rcp_f32_e32 v163, v162
	s_nop 0
	v_fma_f32 v167, -v162, v163, 1.0
	v_fmac_f32_e32 v163, v167, v163
	v_div_scale_f32 v167, vcc, 1.0, v166, 1.0
	v_mul_f32_e32 v168, v167, v163
	v_fma_f32 v182, -v162, v168, v167
	v_fmac_f32_e32 v168, v182, v163
	v_fma_f32 v162, -v162, v168, v167
	v_div_fmas_f32 v162, v162, v163, v168
	v_div_fixup_f32 v182, v162, v166, 1.0
	s_andn2_b64 vcc, exec, s[8:9]
	s_cbranch_vccnz .Lalign_2919
	s_barrier
.Lalign_2919:
	s_mov_b32 s100, 0xbfb8aa3b
	ds_bpermute_b32 v242, v179, v182
	ds_bpermute_b32 v244, v179, v182 offset:64
	ds_bpermute_b32 v246, v179, v182 offset:128
	ds_bpermute_b32 v248, v179, v182 offset:192
	v_mov_b64_e32 v[162:163], s[96:97]
	v_mad_i64_i32 v[166:167], s[2:3], v180, s43, v[162:163]
	v_lshl_add_u64 v[166:167], v[166:167], 0, v[164:165]
	s_waitcnt lgkmcnt(0)
	v_pk_fma_f32 v[142:143], v[142:143], v[242:243], v[78:79] op_sel_hi:[1,0,1]
	v_pk_fma_f32 v[144:145], v[144:145], v[242:243], v[80:81] op_sel_hi:[1,0,1]
	v_pk_fma_f32 v[134:135], v[134:135], v[242:243], v[70:71] op_sel_hi:[1,0,1]
	v_pk_fma_f32 v[136:137], v[136:137], v[242:243], v[72:73] op_sel_hi:[1,0,1]
	v_pk_fma_f32 v[138:139], v[138:139], v[242:243], v[74:75] op_sel_hi:[1,0,1]
	v_pk_fma_f32 v[140:141], v[140:141], v[242:243], v[76:77] op_sel_hi:[1,0,1]
	v_pk_fma_f32 v[130:131], v[130:131], v[242:243], v[66:67] op_sel_hi:[1,0,1]
	v_pk_fma_f32 v[132:133], v[132:133], v[242:243], v[68:69] op_sel_hi:[1,0,1]
	v_pk_mul_f32 v[234:235], v[142:143], s[100:101] op_sel_hi:[1,0]
	v_pk_mul_f32 v[236:237], v[144:145], s[100:101] op_sel_hi:[1,0]
	v_exp_f32_e32 v234, v234
	v_exp_f32_e32 v235, v235
	v_exp_f32_e32 v236, v236
	v_exp_f32_e32 v237, v237
	v_pk_add_f32 v[234:235], v[234:235], 1.0 op_sel_hi:[1,0]
	v_pk_add_f32 v[236:237], v[236:237], 1.0 op_sel_hi:[1,0]
	v_rcp_f32_e32 v234, v234
	v_rcp_f32_e32 v235, v235
	v_rcp_f32_e32 v236, v236
	v_rcp_f32_e32 v237, v237
	v_pk_mul_f32 v[134:135], v[142:143], v[134:135]
	v_pk_mul_f32 v[136:137], v[144:145], v[136:137]
	v_pk_mul_f32 v[134:135], v[134:135], v[234:235]
	v_pk_mul_f32 v[136:137], v[136:137], v[236:237]
	v_cvt_pk_bf16_f32 v238, v134, v135
	v_cvt_pk_bf16_f32 v239, v136, v137
	v_pk_mul_f32 v[234:235], v[138:139], s[100:101] op_sel_hi:[1,0]
	v_pk_mul_f32 v[236:237], v[140:141], s[100:101] op_sel_hi:[1,0]
	v_exp_f32_e32 v234, v234
	v_exp_f32_e32 v235, v235
	v_exp_f32_e32 v236, v236
	v_exp_f32_e32 v237, v237
	v_pk_add_f32 v[234:235], v[234:235], 1.0 op_sel_hi:[1,0]
	v_pk_add_f32 v[236:237], v[236:237], 1.0 op_sel_hi:[1,0]
	v_rcp_f32_e32 v234, v234
	v_rcp_f32_e32 v235, v235
	v_rcp_f32_e32 v236, v236
	v_rcp_f32_e32 v237, v237
	v_pk_mul_f32 v[130:131], v[138:139], v[130:131]
	v_pk_mul_f32 v[132:133], v[140:141], v[132:133]
	v_pk_mul_f32 v[130:131], v[130:131], v[234:235]
	v_pk_mul_f32 v[132:133], v[132:133], v[236:237]
	v_cvt_pk_bf16_f32 v240, v130, v131
	v_cvt_pk_bf16_f32 v241, v132, v133
	global_store_dwordx4 v[166:167], v[238:241], off
	v_or_b32_e32 v131, 16, v180
	v_mad_i64_i32 v[132:133], s[2:3], v131, s43, v[162:163]
	v_lshl_add_u64 v[132:133], v[132:133], 0, v[164:165]
	v_pk_fma_f32 v[126:127], v[126:127], v[244:245], v[78:79] op_sel_hi:[1,0,1]
; __device__ __forceinline__ unsigned cvt_pk_bf16(float lo, float hi) { unsigned r; asm volatile("v_cvt_pk_bf16_f32 %0, %1, %2" : "=v"(r) : "v"(lo), "v"(hi)); return r; }
; __device__ __forceinline__ float silu_mul(float a, float b) { return a * b * __builtin_amdgcn_rcpf(1.0f + __builtin_amdgcn_exp2f(-a * LOG2E)); }
;     __device__ __forceinline__ void operator()(const f32x4 (&acc)[2][2][4][2], const Unit& u, int wr, int wc, int fr, int fq) const {
;     ...
;             for (int m = 0; m < 4; ++m) { const int row = row0 + ai * HALF + m * 16; const float rs = __shfl(ai ? rsl1 : rsl0, m * 16 + fr); bf16_t* rowp = O + (size_t)row * DFF + col0;
;                 const f32x4 a0 = acc[ai][0][m][0] * rs + ba0, a1 = acc[ai][0][m][1] * rs + ba1, b0 = acc[ai][1][m][0] * rs + bb0, b1 = acc[ai][1][m][1] * rs + bb1;
;                 u32x4 w; w.x = cvt_pk_bf16(silu_mul(a0[0], b0[0]), silu_mul(a0[1], b0[1])); w.y = cvt_pk_bf16(silu_mul(a0[2], b0[2]), silu_mul(a0[3], b0[3]));
;                 w.z = cvt_pk_bf16(silu_mul(a1[0], b1[0]), silu_mul(a1[1], b1[1])); w.w = cvt_pk_bf16(silu_mul(a1[2], b1[2]), silu_mul(a1[3], b1[3]));
;                 *(u32x4*)rowp = w; }
	v_pk_fma_f32 v[128:129], v[128:129], v[244:245], v[80:81] op_sel_hi:[1,0,1]
	v_pk_fma_f32 v[118:119], v[118:119], v[244:245], v[70:71] op_sel_hi:[1,0,1]
	v_pk_fma_f32 v[120:121], v[120:121], v[244:245], v[72:73] op_sel_hi:[1,0,1]
	v_pk_fma_f32 v[122:123], v[122:123], v[244:245], v[74:75] op_sel_hi:[1,0,1]
	v_pk_fma_f32 v[124:125], v[124:125], v[244:245], v[76:77] op_sel_hi:[1,0,1]
	v_pk_fma_f32 v[114:115], v[114:115], v[244:245], v[66:67] op_sel_hi:[1,0,1]
	v_pk_fma_f32 v[116:117], v[116:117], v[244:245], v[68:69] op_sel_hi:[1,0,1]
	v_pk_mul_f32 v[234:235], v[126:127], s[100:101] op_sel_hi:[1,0]
	v_pk_mul_f32 v[236:237], v[128:129], s[100:101] op_sel_hi:[1,0]
	v_exp_f32_e32 v234, v234
	v_exp_f32_e32 v235, v235
	v_exp_f32_e32 v236, v236
	v_exp_f32_e32 v237, v237
	v_pk_add_f32 v[234:235], v[234:235], 1.0 op_sel_hi:[1,0]
	v_pk_add_f32 v[236:237], v[236:237], 1.0 op_sel_hi:[1,0]
	v_rcp_f32_e32 v234, v234
	v_rcp_f32_e32 v235, v235
	v_rcp_f32_e32 v236, v236
	v_rcp_f32_e32 v237, v237
	v_pk_mul_f32 v[118:119], v[126:127], v[118:119]
	v_pk_mul_f32 v[120:121], v[128:129], v[120:121]
	v_pk_mul_f32 v[118:119], v[118:119], v[234:235]
	v_pk_mul_f32 v[120:121], v[120:121], v[236:237]
	v_cvt_pk_bf16_f32 v238, v118, v119
	v_cvt_pk_bf16_f32 v239, v120, v121
	v_pk_mul_f32 v[234:235], v[122:123], s[100:101] op_sel_hi:[1,0]
	v_pk_mul_f32 v[236:237], v[124:125], s[100:101] op_sel_hi:[1,0]
	v_exp_f32_e32 v234, v234
	v_exp_f32_e32 v235, v235
	v_exp_f32_e32 v236, v236
	v_exp_f32_e32 v237, v237
	v_pk_add_f32 v[234:235], v[234:235], 1.0 op_sel_hi:[1,0]
	v_pk_add_f32 v[236:237], v[236:237], 1.0 op_sel_hi:[1,0]
	v_rcp_f32_e32 v234, v234
	v_rcp_f32_e32 v235, v235
	v_rcp_f32_e32 v236, v236
	v_rcp_f32_e32 v237, v237
	v_pk_mul_f32 v[114:115], v[122:123], v[114:115]
	v_pk_mul_f32 v[116:117], v[124:125], v[116:117]
	v_pk_mul_f32 v[114:115], v[114:115], v[234:235]
	v_pk_mul_f32 v[116:117], v[116:117], v[236:237]
	v_cvt_pk_bf16_f32 v240, v114, v115
	v_cvt_pk_bf16_f32 v241, v116, v117
	global_store_dwordx4 v[132:133], v[238:241], off
	v_or_b32_e32 v115, 32, v180
	v_mad_i64_i32 v[116:117], s[2:3], v115, s43, v[162:163]
	v_lshl_add_u64 v[116:117], v[116:117], 0, v[164:165]
	v_pk_fma_f32 v[110:111], v[110:111], v[246:247], v[78:79] op_sel_hi:[1,0,1]
	v_pk_fma_f32 v[112:113], v[112:113], v[246:247], v[80:81] op_sel_hi:[1,0,1]
	v_pk_fma_f32 v[102:103], v[102:103], v[246:247], v[70:71] op_sel_hi:[1,0,1]
	v_pk_fma_f32 v[104:105], v[104:105], v[246:247], v[72:73] op_sel_hi:[1,0,1]
	v_pk_fma_f32 v[106:107], v[106:107], v[246:247], v[74:75] op_sel_hi:[1,0,1]
	v_pk_fma_f32 v[108:109], v[108:109], v[246:247], v[76:77] op_sel_hi:[1,0,1]
	v_pk_fma_f32 v[98:99], v[98:99], v[246:247], v[66:67] op_sel_hi:[1,0,1]
	v_pk_fma_f32 v[100:101], v[100:101], v[246:247], v[68:69] op_sel_hi:[1,0,1]
	v_pk_mul_f32 v[234:235], v[110:111], s[100:101] op_sel_hi:[1,0]
	v_pk_mul_f32 v[236:237], v[112:113], s[100:101] op_sel_hi:[1,0]
	v_exp_f32_e32 v234, v234
	v_exp_f32_e32 v235, v235
	v_exp_f32_e32 v236, v236
	v_exp_f32_e32 v237, v237
	v_pk_add_f32 v[234:235], v[234:235], 1.0 op_sel_hi:[1,0]
	v_pk_add_f32 v[236:237], v[236:237], 1.0 op_sel_hi:[1,0]
	v_rcp_f32_e32 v234, v234
	v_rcp_f32_e32 v235, v235
	v_rcp_f32_e32 v236, v236
	v_rcp_f32_e32 v237, v237
	v_pk_mul_f32 v[102:103], v[110:111], v[102:103]
	v_pk_mul_f32 v[104:105], v[112:113], v[104:105]
	v_pk_mul_f32 v[102:103], v[102:103], v[234:235]
	v_pk_mul_f32 v[104:105], v[104:105], v[236:237]
	v_cvt_pk_bf16_f32 v238, v102, v103
	v_cvt_pk_bf16_f32 v239, v104, v105
	v_pk_mul_f32 v[234:235], v[106:107], s[100:101] op_sel_hi:[1,0]
	v_pk_mul_f32 v[236:237], v[108:109], s[100:101] op_sel_hi:[1,0]
	v_exp_f32_e32 v234, v234
	v_exp_f32_e32 v235, v235
	v_exp_f32_e32 v236, v236
	v_exp_f32_e32 v237, v237
	v_pk_add_f32 v[234:235], v[234:235], 1.0 op_sel_hi:[1,0]
	v_pk_add_f32 v[236:237], v[236:237], 1.0 op_sel_hi:[1,0]
	v_rcp_f32_e32 v234, v234
	v_rcp_f32_e32 v235, v235
	v_rcp_f32_e32 v236, v236
	v_rcp_f32_e32 v237, v237
	v_pk_mul_f32 v[98:99], v[106:107], v[98:99]
	v_pk_mul_f32 v[100:101], v[108:109], v[100:101]
	v_pk_mul_f32 v[98:99], v[98:99], v[234:235]
	v_pk_mul_f32 v[100:101], v[100:101], v[236:237]
	v_cvt_pk_bf16_f32 v240, v98, v99
	v_cvt_pk_bf16_f32 v241, v100, v101
	global_store_dwordx4 v[116:117], v[238:241], off
	v_or_b32_e32 v99, 48, v180
	v_mad_i64_i32 v[100:101], s[2:3], v99, s43, v[162:163]
	v_lshl_add_u64 v[100:101], v[100:101], 0, v[164:165]
	v_pk_fma_f32 v[94:95], v[94:95], v[248:249], v[78:79] op_sel_hi:[1,0,1]
	v_pk_fma_f32 v[96:97], v[96:97], v[248:249], v[80:81] op_sel_hi:[1,0,1]
	v_pk_fma_f32 v[86:87], v[86:87], v[248:249], v[70:71] op_sel_hi:[1,0,1]
	v_pk_fma_f32 v[88:89], v[88:89], v[248:249], v[72:73] op_sel_hi:[1,0,1]
	v_pk_fma_f32 v[90:91], v[90:91], v[248:249], v[74:75] op_sel_hi:[1,0,1]
	v_pk_fma_f32 v[92:93], v[92:93], v[248:249], v[76:77] op_sel_hi:[1,0,1]
	v_pk_fma_f32 v[82:83], v[82:83], v[248:249], v[66:67] op_sel_hi:[1,0,1]
	v_pk_fma_f32 v[84:85], v[84:85], v[248:249], v[68:69] op_sel_hi:[1,0,1]
	v_pk_mul_f32 v[234:235], v[94:95], s[100:101] op_sel_hi:[1,0]
	v_pk_mul_f32 v[236:237], v[96:97], s[100:101] op_sel_hi:[1,0]
	v_exp_f32_e32 v234, v234
	v_exp_f32_e32 v235, v235
	v_exp_f32_e32 v236, v236
	v_exp_f32_e32 v237, v237
	v_pk_add_f32 v[234:235], v[234:235], 1.0 op_sel_hi:[1,0]
	v_pk_add_f32 v[236:237], v[236:237], 1.0 op_sel_hi:[1,0]
	v_rcp_f32_e32 v234, v234
	v_rcp_f32_e32 v235, v235
	v_rcp_f32_e32 v236, v236
	v_rcp_f32_e32 v237, v237
	v_pk_mul_f32 v[86:87], v[94:95], v[86:87]
	v_pk_mul_f32 v[88:89], v[96:97], v[88:89]
	v_pk_mul_f32 v[86:87], v[86:87], v[234:235]
	v_pk_mul_f32 v[88:89], v[88:89], v[236:237]
	v_cvt_pk_bf16_f32 v238, v86, v87
; __device__ __forceinline__ unsigned cvt_pk_bf16(float lo, float hi) { unsigned r; asm volatile("v_cvt_pk_bf16_f32 %0, %1, %2" : "=v"(r) : "v"(lo), "v"(hi)); return r; }
; __device__ __forceinline__ float row_rstd(const float* ss, int row) { return 1.0f / sqrtf(ss[row] * (1.0f / DM) + 1e-6f); }
; __device__ __forceinline__ float silu_mul(float a, float b) { return a * b * __builtin_amdgcn_rcpf(1.0f + __builtin_amdgcn_exp2f(-a * LOG2E)); }
;     __device__ __forceinline__ void operator()(const f32x4 (&acc)[2][2][4][2], const Unit& u, int wr, int wc, int fr, int fq) const {
;     ...
;         const float rsl0 = row_rstd(ss, u.pm * BM + wr * 64 + lane), rsl1 = row_rstd(ss, u.pm * BM + HALF + wr * 64 + lane);
; #pragma unroll
;         for (int ai = 0; ai < 2; ++ai)
; #pragma unroll
;             for (int m = 0; m < 4; ++m) { const int row = row0 + ai * HALF + m * 16; const float rs = __shfl(ai ? rsl1 : rsl0, m * 16 + fr); bf16_t* rowp = O + (size_t)row * DFF + col0;
;                 const f32x4 a0 = acc[ai][0][m][0] * rs + ba0, a1 = acc[ai][0][m][1] * rs + ba1, b0 = acc[ai][1][m][0] * rs + bb0, b1 = acc[ai][1][m][1] * rs + bb1;
;                 u32x4 w; w.x = cvt_pk_bf16(silu_mul(a0[0], b0[0]), silu_mul(a0[1], b0[1])); w.y = cvt_pk_bf16(silu_mul(a0[2], b0[2]), silu_mul(a0[3], b0[3]));
;                 w.z = cvt_pk_bf16(silu_mul(a1[0], b1[0]), silu_mul(a1[1], b1[1])); w.w = cvt_pk_bf16(silu_mul(a1[2], b1[2]), silu_mul(a1[3], b1[3]));
;                 *(u32x4*)rowp = w; }
	v_cvt_pk_bf16_f32 v239, v88, v89
	v_pk_mul_f32 v[234:235], v[90:91], s[100:101] op_sel_hi:[1,0]
	v_pk_mul_f32 v[236:237], v[92:93], s[100:101] op_sel_hi:[1,0]
	v_exp_f32_e32 v234, v234
	v_exp_f32_e32 v235, v235
	v_exp_f32_e32 v236, v236
	v_exp_f32_e32 v237, v237
	v_pk_add_f32 v[234:235], v[234:235], 1.0 op_sel_hi:[1,0]
	v_pk_add_f32 v[236:237], v[236:237], 1.0 op_sel_hi:[1,0]
	v_rcp_f32_e32 v234, v234
	v_rcp_f32_e32 v235, v235
	v_rcp_f32_e32 v236, v236
	v_rcp_f32_e32 v237, v237
	v_pk_mul_f32 v[82:83], v[90:91], v[82:83]
	v_pk_mul_f32 v[84:85], v[92:93], v[84:85]
	v_pk_mul_f32 v[82:83], v[82:83], v[234:235]
	v_pk_mul_f32 v[84:85], v[84:85], v[236:237]
	v_cvt_pk_bf16_f32 v240, v82, v83
	v_cvt_pk_bf16_f32 v241, v84, v85
	global_store_dwordx4 v[100:101], v[238:241], off
	s_nop 1
	v_div_scale_f32 v82, s[2:3], v181, v181, 1.0
	v_rcp_f32_e32 v84, v82
	v_add_u32_e32 v83, 0x80, v180
	v_fma_f32 v85, -v82, v84, 1.0
	v_fmac_f32_e32 v84, v85, v84
	v_div_scale_f32 v85, vcc, 1.0, v181, 1.0
	v_mul_f32_e32 v86, v85, v84
	v_fma_f32 v87, -v82, v86, v85
	v_fmac_f32_e32 v86, v87, v84
	v_fma_f32 v82, -v82, v86, v85
	v_div_fmas_f32 v82, v82, v84, v86
	v_div_fixup_f32 v82, v82, v181, 1.0
	ds_bpermute_b32 v242, v179, v82
	ds_bpermute_b32 v244, v179, v82 offset:64
	ds_bpermute_b32 v246, v179, v82 offset:128
	ds_bpermute_b32 v248, v179, v82 offset:192
	v_mad_i64_i32 v[86:87], s[2:3], v83, s43, v[162:163]
	v_lshl_add_u64 v[86:87], v[86:87], 0, v[164:165]
	s_and_b64 vcc, s[36:37], exec
	s_waitcnt lgkmcnt(0)
	v_pk_fma_f32 v[62:63], v[62:63], v[242:243], v[78:79] op_sel_hi:[1,0,1]
	v_pk_fma_f32 v[64:65], v[64:65], v[242:243], v[80:81] op_sel_hi:[1,0,1]
	v_pk_fma_f32 v[54:55], v[54:55], v[242:243], v[70:71] op_sel_hi:[1,0,1]
	v_pk_fma_f32 v[56:57], v[56:57], v[242:243], v[72:73] op_sel_hi:[1,0,1]
	v_pk_fma_f32 v[58:59], v[58:59], v[242:243], v[74:75] op_sel_hi:[1,0,1]
	v_pk_fma_f32 v[60:61], v[60:61], v[242:243], v[76:77] op_sel_hi:[1,0,1]
	v_pk_fma_f32 v[50:51], v[50:51], v[242:243], v[66:67] op_sel_hi:[1,0,1]
	v_pk_fma_f32 v[52:53], v[52:53], v[242:243], v[68:69] op_sel_hi:[1,0,1]
	v_pk_mul_f32 v[234:235], v[62:63], s[100:101] op_sel_hi:[1,0]
	v_pk_mul_f32 v[236:237], v[64:65], s[100:101] op_sel_hi:[1,0]
	v_exp_f32_e32 v234, v234
	v_exp_f32_e32 v235, v235
	v_exp_f32_e32 v236, v236
	v_exp_f32_e32 v237, v237
	v_pk_add_f32 v[234:235], v[234:235], 1.0 op_sel_hi:[1,0]
	v_pk_add_f32 v[236:237], v[236:237], 1.0 op_sel_hi:[1,0]
	v_rcp_f32_e32 v234, v234
	v_rcp_f32_e32 v235, v235
	v_rcp_f32_e32 v236, v236
	v_rcp_f32_e32 v237, v237
	v_pk_mul_f32 v[54:55], v[62:63], v[54:55]
	v_pk_mul_f32 v[56:57], v[64:65], v[56:57]
	v_pk_mul_f32 v[54:55], v[54:55], v[234:235]
	v_pk_mul_f32 v[56:57], v[56:57], v[236:237]
	v_cvt_pk_bf16_f32 v238, v54, v55
	v_cvt_pk_bf16_f32 v239, v56, v57
	v_pk_mul_f32 v[234:235], v[58:59], s[100:101] op_sel_hi:[1,0]
	v_pk_mul_f32 v[236:237], v[60:61], s[100:101] op_sel_hi:[1,0]
	v_exp_f32_e32 v234, v234
	v_exp_f32_e32 v235, v235
	v_exp_f32_e32 v236, v236
	v_exp_f32_e32 v237, v237
	v_pk_add_f32 v[234:235], v[234:235], 1.0 op_sel_hi:[1,0]
	v_pk_add_f32 v[236:237], v[236:237], 1.0 op_sel_hi:[1,0]
	v_rcp_f32_e32 v234, v234
	v_rcp_f32_e32 v235, v235
	v_rcp_f32_e32 v236, v236
	v_rcp_f32_e32 v237, v237
	v_pk_mul_f32 v[50:51], v[58:59], v[50:51]
	v_pk_mul_f32 v[52:53], v[60:61], v[52:53]
	v_pk_mul_f32 v[50:51], v[50:51], v[234:235]
	v_pk_mul_f32 v[52:53], v[52:53], v[236:237]
	v_cvt_pk_bf16_f32 v240, v50, v51
	v_cvt_pk_bf16_f32 v241, v52, v53
	global_store_dwordx4 v[86:87], v[238:241], off
	v_add_u32_e32 v51, 0x90, v180
	v_mad_i64_i32 v[52:53], s[2:3], v51, s43, v[162:163]
	v_lshl_add_u64 v[52:53], v[52:53], 0, v[164:165]
	v_pk_fma_f32 v[46:47], v[46:47], v[244:245], v[78:79] op_sel_hi:[1,0,1]
	v_pk_fma_f32 v[48:49], v[48:49], v[244:245], v[80:81] op_sel_hi:[1,0,1]
	v_pk_fma_f32 v[38:39], v[38:39], v[244:245], v[70:71] op_sel_hi:[1,0,1]
	v_pk_fma_f32 v[40:41], v[40:41], v[244:245], v[72:73] op_sel_hi:[1,0,1]
	v_pk_fma_f32 v[42:43], v[42:43], v[244:245], v[74:75] op_sel_hi:[1,0,1]
	v_pk_fma_f32 v[44:45], v[44:45], v[244:245], v[76:77] op_sel_hi:[1,0,1]
	v_pk_fma_f32 v[34:35], v[34:35], v[244:245], v[66:67] op_sel_hi:[1,0,1]
	v_pk_fma_f32 v[36:37], v[36:37], v[244:245], v[68:69] op_sel_hi:[1,0,1]
	v_pk_mul_f32 v[234:235], v[46:47], s[100:101] op_sel_hi:[1,0]
	v_pk_mul_f32 v[236:237], v[48:49], s[100:101] op_sel_hi:[1,0]
	v_exp_f32_e32 v234, v234
	v_exp_f32_e32 v235, v235
	v_exp_f32_e32 v236, v236
	v_exp_f32_e32 v237, v237
	v_pk_add_f32 v[234:235], v[234:235], 1.0 op_sel_hi:[1,0]
	v_pk_add_f32 v[236:237], v[236:237], 1.0 op_sel_hi:[1,0]
	v_rcp_f32_e32 v234, v234
	v_rcp_f32_e32 v235, v235
	v_rcp_f32_e32 v236, v236
	v_rcp_f32_e32 v237, v237
	v_pk_mul_f32 v[38:39], v[46:47], v[38:39]
	v_pk_mul_f32 v[40:41], v[48:49], v[40:41]
	v_pk_mul_f32 v[38:39], v[38:39], v[234:235]
	v_pk_mul_f32 v[40:41], v[40:41], v[236:237]
	v_cvt_pk_bf16_f32 v238, v38, v39
	v_cvt_pk_bf16_f32 v239, v40, v41
	v_pk_mul_f32 v[234:235], v[42:43], s[100:101] op_sel_hi:[1,0]
	v_pk_mul_f32 v[236:237], v[44:45], s[100:101] op_sel_hi:[1,0]
; __device__ __forceinline__ unsigned cvt_pk_bf16(float lo, float hi) { unsigned r; asm volatile("v_cvt_pk_bf16_f32 %0, %1, %2" : "=v"(r) : "v"(lo), "v"(hi)); return r; }
; __device__ __forceinline__ float silu_mul(float a, float b) { return a * b * __builtin_amdgcn_rcpf(1.0f + __builtin_amdgcn_exp2f(-a * LOG2E)); }
; #define PG8_BAR __builtin_amdgcn_s_barrier()
;     __device__ __forceinline__ void operator()(const f32x4 (&acc)[2][2][4][2], const Unit& u, int wr, int wc, int fr, int fq) const {
;     ...
;             for (int m = 0; m < 4; ++m) { const int row = row0 + ai * HALF + m * 16; const float rs = __shfl(ai ? rsl1 : rsl0, m * 16 + fr); bf16_t* rowp = O + (size_t)row * DFF + col0;
;                 const f32x4 a0 = acc[ai][0][m][0] * rs + ba0, a1 = acc[ai][0][m][1] * rs + ba1, b0 = acc[ai][1][m][0] * rs + bb0, b1 = acc[ai][1][m][1] * rs + bb1;
;                 u32x4 w; w.x = cvt_pk_bf16(silu_mul(a0[0], b0[0]), silu_mul(a0[1], b0[1])); w.y = cvt_pk_bf16(silu_mul(a0[2], b0[2]), silu_mul(a0[3], b0[3]));
;                 w.z = cvt_pk_bf16(silu_mul(a1[0], b1[0]), silu_mul(a1[1], b1[1])); w.w = cvt_pk_bf16(silu_mul(a1[2], b1[2]), silu_mul(a1[3], b1[3]));
;                 *(u32x4*)rowp = w; }
; template <class Epi, class Sched, bool ALIGN_EPI = false, bool SP2 = false>
; __device__ __forceinline__ void gemm_phase(LAS unsigned char* lds, const Gemm g, const Sched& S, const Epi& E) {
;     ...
;         if constexpr (!Epi::AFTER_DRAIN) { E(acc, cur, wr, wc, fr, fq); S.done(cur); }
;         if (!has_next) break;
; #pragma unroll
;         for (int a = 0; a < 2; ++a)
; #pragma unroll
;             for (int b = 0; b < 2; ++b)
; #pragma unroll
;                 for (int m = 0; m < 4; ++m)
; #pragma unroll
;                     for (int n = 0; n < 2; ++n) acc[a][b][m][n] = (f32x4){0.f, 0.f, 0.f, 0.f};
;         cur = nxt; cA = nA; cB = nB; ++ui;
;         if constexpr (ALIGN_EPI) { if (wr == 1) PG8_BAR; }
	v_exp_f32_e32 v234, v234
	v_exp_f32_e32 v235, v235
	v_exp_f32_e32 v236, v236
	v_exp_f32_e32 v237, v237
	v_pk_add_f32 v[234:235], v[234:235], 1.0 op_sel_hi:[1,0]
	v_pk_add_f32 v[236:237], v[236:237], 1.0 op_sel_hi:[1,0]
	v_rcp_f32_e32 v234, v234
	v_rcp_f32_e32 v235, v235
	v_rcp_f32_e32 v236, v236
	v_rcp_f32_e32 v237, v237
	v_pk_mul_f32 v[34:35], v[42:43], v[34:35]
	v_pk_mul_f32 v[36:37], v[44:45], v[36:37]
	v_pk_mul_f32 v[34:35], v[34:35], v[234:235]
	v_pk_mul_f32 v[36:37], v[36:37], v[236:237]
	v_cvt_pk_bf16_f32 v240, v34, v35
	v_cvt_pk_bf16_f32 v241, v36, v37
	global_store_dwordx4 v[52:53], v[238:241], off
	v_add_u32_e32 v35, 0xa0, v180
	v_mad_i64_i32 v[36:37], s[2:3], v35, s43, v[162:163]
	v_lshl_add_u64 v[36:37], v[36:37], 0, v[164:165]
	v_pk_fma_f32 v[30:31], v[30:31], v[246:247], v[78:79] op_sel_hi:[1,0,1]
	v_pk_fma_f32 v[32:33], v[32:33], v[246:247], v[80:81] op_sel_hi:[1,0,1]
	v_pk_fma_f32 v[22:23], v[22:23], v[246:247], v[70:71] op_sel_hi:[1,0,1]
	v_pk_fma_f32 v[24:25], v[24:25], v[246:247], v[72:73] op_sel_hi:[1,0,1]
	v_pk_fma_f32 v[26:27], v[26:27], v[246:247], v[74:75] op_sel_hi:[1,0,1]
	v_pk_fma_f32 v[28:29], v[28:29], v[246:247], v[76:77] op_sel_hi:[1,0,1]
	v_pk_fma_f32 v[18:19], v[18:19], v[246:247], v[66:67] op_sel_hi:[1,0,1]
	v_pk_fma_f32 v[20:21], v[20:21], v[246:247], v[68:69] op_sel_hi:[1,0,1]
	v_pk_mul_f32 v[234:235], v[30:31], s[100:101] op_sel_hi:[1,0]
	v_pk_mul_f32 v[236:237], v[32:33], s[100:101] op_sel_hi:[1,0]
	v_exp_f32_e32 v234, v234
	v_exp_f32_e32 v235, v235
	v_exp_f32_e32 v236, v236
	v_exp_f32_e32 v237, v237
	v_pk_add_f32 v[234:235], v[234:235], 1.0 op_sel_hi:[1,0]
	v_pk_add_f32 v[236:237], v[236:237], 1.0 op_sel_hi:[1,0]
	v_rcp_f32_e32 v234, v234
	v_rcp_f32_e32 v235, v235
	v_rcp_f32_e32 v236, v236
	v_rcp_f32_e32 v237, v237
	v_pk_mul_f32 v[22:23], v[30:31], v[22:23]
	v_pk_mul_f32 v[24:25], v[32:33], v[24:25]
	v_pk_mul_f32 v[22:23], v[22:23], v[234:235]
	v_pk_mul_f32 v[24:25], v[24:25], v[236:237]
	v_cvt_pk_bf16_f32 v238, v22, v23
	v_cvt_pk_bf16_f32 v239, v24, v25
	v_pk_mul_f32 v[234:235], v[26:27], s[100:101] op_sel_hi:[1,0]
	v_pk_mul_f32 v[236:237], v[28:29], s[100:101] op_sel_hi:[1,0]
	v_exp_f32_e32 v234, v234
	v_exp_f32_e32 v235, v235
	v_exp_f32_e32 v236, v236
	v_exp_f32_e32 v237, v237
	v_pk_add_f32 v[234:235], v[234:235], 1.0 op_sel_hi:[1,0]
	v_pk_add_f32 v[236:237], v[236:237], 1.0 op_sel_hi:[1,0]
	v_rcp_f32_e32 v234, v234
	v_rcp_f32_e32 v235, v235
	v_rcp_f32_e32 v236, v236
	v_rcp_f32_e32 v237, v237
	v_pk_mul_f32 v[18:19], v[26:27], v[18:19]
	v_pk_mul_f32 v[20:21], v[28:29], v[20:21]
	v_pk_mul_f32 v[18:19], v[18:19], v[234:235]
	v_pk_mul_f32 v[20:21], v[20:21], v[236:237]
	v_cvt_pk_bf16_f32 v240, v18, v19
	v_cvt_pk_bf16_f32 v241, v20, v21
	global_store_dwordx4 v[36:37], v[238:241], off
	v_add_u32_e32 v19, 0xb0, v180
	v_mad_i64_i32 v[20:21], s[2:3], v19, s43, v[162:163]
	v_lshl_add_u64 v[20:21], v[20:21], 0, v[164:165]
	s_mov_b64 s[2:3], -1
	v_pk_fma_f32 v[14:15], v[14:15], v[248:249], v[78:79] op_sel_hi:[1,0,1]
	v_pk_fma_f32 v[16:17], v[16:17], v[248:249], v[80:81] op_sel_hi:[1,0,1]
	v_pk_fma_f32 v[6:7], v[6:7], v[248:249], v[70:71] op_sel_hi:[1,0,1]
	v_pk_fma_f32 v[8:9], v[8:9], v[248:249], v[72:73] op_sel_hi:[1,0,1]
	v_pk_fma_f32 v[10:11], v[10:11], v[248:249], v[74:75] op_sel_hi:[1,0,1]
	v_pk_fma_f32 v[12:13], v[12:13], v[248:249], v[76:77] op_sel_hi:[1,0,1]
	v_pk_fma_f32 v[2:3], v[2:3], v[248:249], v[66:67] op_sel_hi:[1,0,1]
	v_pk_fma_f32 v[4:5], v[4:5], v[248:249], v[68:69] op_sel_hi:[1,0,1]
	v_pk_mul_f32 v[234:235], v[14:15], s[100:101] op_sel_hi:[1,0]
	v_pk_mul_f32 v[236:237], v[16:17], s[100:101] op_sel_hi:[1,0]
	v_exp_f32_e32 v234, v234
	v_exp_f32_e32 v235, v235
	v_exp_f32_e32 v236, v236
	v_exp_f32_e32 v237, v237
	v_pk_add_f32 v[234:235], v[234:235], 1.0 op_sel_hi:[1,0]
	v_pk_add_f32 v[236:237], v[236:237], 1.0 op_sel_hi:[1,0]
	v_rcp_f32_e32 v234, v234
	v_rcp_f32_e32 v235, v235
	v_rcp_f32_e32 v236, v236
	v_rcp_f32_e32 v237, v237
	v_pk_mul_f32 v[6:7], v[14:15], v[6:7]
	v_pk_mul_f32 v[8:9], v[16:17], v[8:9]
	v_pk_mul_f32 v[6:7], v[6:7], v[234:235]
	v_pk_mul_f32 v[8:9], v[8:9], v[236:237]
	v_cvt_pk_bf16_f32 v238, v6, v7
	v_cvt_pk_bf16_f32 v239, v8, v9
	v_pk_mul_f32 v[234:235], v[10:11], s[100:101] op_sel_hi:[1,0]
	v_pk_mul_f32 v[236:237], v[12:13], s[100:101] op_sel_hi:[1,0]
	v_exp_f32_e32 v234, v234
	v_exp_f32_e32 v235, v235
	v_exp_f32_e32 v236, v236
	v_exp_f32_e32 v237, v237
	v_pk_add_f32 v[234:235], v[234:235], 1.0 op_sel_hi:[1,0]
	v_pk_add_f32 v[236:237], v[236:237], 1.0 op_sel_hi:[1,0]
	v_rcp_f32_e32 v234, v234
	v_rcp_f32_e32 v235, v235
	v_rcp_f32_e32 v236, v236
	v_rcp_f32_e32 v237, v237
	v_pk_mul_f32 v[2:3], v[10:11], v[2:3]
	v_pk_mul_f32 v[4:5], v[12:13], v[4:5]
	v_pk_mul_f32 v[2:3], v[2:3], v[234:235]
	v_pk_mul_f32 v[4:5], v[4:5], v[236:237]
	v_cvt_pk_bf16_f32 v240, v2, v3
	v_cvt_pk_bf16_f32 v241, v4, v5
	global_store_dwordx4 v[20:21], v[238:241], off
	s_waitcnt vmcnt(8)
	s_cbranch_vccz .LBB0_2912
	s_andn2_b64 vcc, exec, s[4:5]
	s_cbranch_vccnz .LBB0_2911
	s_barrier
	s_branch .LBB0_2911
